# retout: Toeplitz decay factors from a per-item 255-entry LDS table (same op sequence, one entry per thread) instead of 63 per-element chains with 2 exps each; reads software-pipelined 3 ahead
# speedup vs baseline: 1.0131x; 1.0131x over previous
.LBB0_120:
	v_lshrrev_b32_e32 v11, 3, v52
	v_lshrrev_b32_e32 v12, 1, v53
	v_bfe_u32 v13, v53, 1, 3
	v_bitop3_b32 v12, v11, v12, 7 bitop3:0x78
	v_lshlrev_b32_e32 v14, 1, v50
	v_lshl_or_b32 v12, v12, 4, v14
	v_bitop3_b32 v11, v11, v13, 1 bitop3:0x36
	v_cvt_pk_bf16_f32 v2, v84, v85
	v_cvt_pk_bf16_f32 v3, v82, v83
	v_cvt_pk_bf16_f32 v4, v80, v81
	v_cvt_pk_bf16_f32 v5, v78, v79
	v_add_u32_e32 v12, 0, v12
	v_lshl_or_b32 v11, v11, 4, v14
	v_lshrrev_b32_e32 v10, 4, v133
	s_ashr_i32 s1, s3, 6
	v_cvt_pk_bf16_f32 v6, v74, v75
	v_cvt_pk_bf16_f32 v7, v72, v73
	v_cvt_pk_bf16_f32 v8, v70, v71
	v_cvt_pk_bf16_f32 v9, v68, v69
	ds_write_b128 v12, v[2:5] offset:49152
	ds_write_b128 v12, v[6:9] offset:57344
	v_cvt_pk_bf16_f32 v2, v76, v77
	v_cvt_pk_bf16_f32 v3, v66, v67
	v_cvt_pk_bf16_f32 v4, v64, v65
	v_cvt_pk_bf16_f32 v5, v54, v55
	v_add_u32_e32 v11, 0, v11
	v_bfe_u32 v78, v133, 1, 3
	v_and_b32_e32 v0, 15, v133
	v_cvt_pk_bf16_f32 v6, v62, v63
	v_cvt_pk_bf16_f32 v7, v60, v61
	v_cvt_pk_bf16_f32 v8, v58, v59
	v_cvt_pk_bf16_f32 v9, v56, v57
	ds_write_b128 v11, v[2:5] offset:49152
	ds_write_b128 v11, v[6:9] offset:57344
	v_bitop3_b32 v2, v10, v78, 3 bitop3:0x6c
	s_lshl_b32 s0, s1, 12
	s_add_i32 s3, s0, 0
	v_lshlrev_b32_e32 v134, 7, v0
	v_lshlrev_b32_e32 v135, 4, v2
	v_add_u32_e32 v79, s3, v134
	v_or_b32_e32 v10, v135, v134
	v_add_u32_e32 v6, v79, v135
	v_add_u32_e32 v80, 0, v10
	s_waitcnt lgkmcnt(0)
	s_barrier
	ds_read_b128 v[2:5], v6
	ds_read_b128 v[6:9], v6 offset:2048
	ds_read_b128 v[10:13], v80 offset:16384
	ds_read_b128 v[18:21], v80 offset:18432
	ds_read_b128 v[26:29], v80 offset:20480
	ds_read_b128 v[34:37], v80 offset:22528
	ds_read_b128 v[42:45], v80 offset:24576
	ds_read_b128 v[50:53], v80 offset:26624
	ds_read_b128 v[58:61], v80 offset:28672
	ds_read_b128 v[66:69], v80 offset:30720
	ds_read_b128 v[70:73], v80 offset:49152
	ds_read_b128 v[74:77], v80 offset:57344
	s_waitcnt lgkmcnt(1)
	v_mfma_f32_16x16x32_bf16 v[138:141], v[2:5], v[70:73], 0
	v_bfe_u32 v132, v133, 4, 2
	v_lshlrev_b32_e32 v133, 1, v133
	s_movk_i32 s3, 0x1200
	s_waitcnt lgkmcnt(0)
	v_mfma_f32_16x16x32_bf16 v[142:145], v[2:5], v[74:77], 0
	s_mov_b64 s[10:11], 0x1000
	s_movk_i32 s7, 0x1000
	s_mov_b32 s12, 0x3c800000
	v_mfma_f32_16x16x32_bf16 v[146:149], v[6:9], v[70:73], 0
	s_mov_b32 s8, 0x800000
	s_mov_b64 s[34:35], -1
	v_mfma_f32_16x16x32_bf16 v[150:153], v[6:9], v[74:77], 0
	ds_read_b128 v[70:73], v80 offset:51200
	ds_read_b128 v[74:77], v80 offset:59392
	s_waitcnt lgkmcnt(1)
	v_mfma_f32_16x16x32_bf16 v[154:157], v[2:5], v[70:73], 0
	s_waitcnt lgkmcnt(0)
	v_mfma_f32_16x16x32_bf16 v[158:161], v[2:5], v[74:77], 0
	v_mfma_f32_16x16x32_bf16 v[162:165], v[6:9], v[70:73], 0
	v_mfma_f32_16x16x32_bf16 v[166:169], v[6:9], v[74:77], 0
	ds_read_b128 v[70:73], v80 offset:53248
	ds_read_b128 v[74:77], v80 offset:61440
	s_waitcnt lgkmcnt(1)
	v_mfma_f32_16x16x32_bf16 v[170:173], v[2:5], v[70:73], 0
	s_waitcnt lgkmcnt(0)
	v_mfma_f32_16x16x32_bf16 v[176:179], v[2:5], v[74:77], 0
	v_mfma_f32_16x16x32_bf16 v[180:183], v[6:9], v[70:73], 0
	v_mfma_f32_16x16x32_bf16 v[184:187], v[6:9], v[74:77], 0
	ds_read_b128 v[70:73], v80 offset:55296
	ds_read_b128 v[74:77], v80 offset:63488
	v_mfma_f32_16x16x32_bf16 v[14:17], v[2:5], v[10:13], 0
	v_mfma_f32_16x16x32_bf16 v[22:25], v[2:5], v[18:21], 0
	v_mfma_f32_16x16x32_bf16 v[30:33], v[2:5], v[26:29], 0
	v_mfma_f32_16x16x32_bf16 v[38:41], v[2:5], v[34:37], 0
	v_mfma_f32_16x16x32_bf16 v[46:49], v[2:5], v[42:45], 0
	v_mfma_f32_16x16x32_bf16 v[54:57], v[2:5], v[50:53], 0
	v_mfma_f32_16x16x32_bf16 v[62:65], v[2:5], v[58:61], 0
	v_mfma_f32_16x16x32_bf16 v[98:101], v[2:5], v[66:69], 0
	s_waitcnt lgkmcnt(1)
	v_mfma_f32_16x16x32_bf16 v[188:191], v[2:5], v[70:73], 0
	s_waitcnt lgkmcnt(0)
	v_mfma_f32_16x16x32_bf16 v[192:195], v[2:5], v[74:77], 0
	v_bitop3_b32 v2, v132, v78, 4 bitop3:0x36
	v_lshlrev_b32_e32 v136, 4, v2
	v_add_u32_e32 v2, v79, v136
	ds_read_b128 v[208:211], v2
	ds_read_b128 v[212:215], v2 offset:2048
	v_or_b32_e32 v2, v136, v134
	v_add_u32_e32 v137, 0, v2
	ds_read_b128 v[2:5], v137 offset:16384
	v_mfma_f32_16x16x32_bf16 v[10:13], v[6:9], v[10:13], 0
	v_lshlrev_b32_e32 v132, 2, v132
	v_lshl_or_b32 v132, s1, 5, v132
	v_and_b32_e32 v232, 15, v207
	v_lshlrev_b32_e32 v232, 1, v232
	v_mov_b32_e32 v233, 0
	v_mov_b32_e32 v247, 0
	v_or_b32_e32 v246, 0, v132
	v_add_u32_e32 v246, s6, v246
	v_mul_u32_u24_e32 v246, 0x1200, v246
	v_lshl_add_u64 v[248:249], s[92:93], 0, v[246:247]
	v_lshl_add_u64 v[248:249], v[248:249], 0, s[26:27]
	v_lshl_add_u64 v[248:249], v[248:249], 0, v[232:233]
	v_lshl_add_u64 v[248:249], v[248:249], 0, s[10:11]
	global_load_ushort v216, v[248:249], off
	global_load_ushort v217, v[248:249], off offset:32
	global_load_ushort v218, v[248:249], off offset:64
	global_load_ushort v219, v[248:249], off offset:96
	v_or_b32_e32 v246, 1, v132
	v_add_u32_e32 v246, s6, v246
	v_mul_u32_u24_e32 v246, 0x1200, v246
	v_lshl_add_u64 v[248:249], s[92:93], 0, v[246:247]
	v_lshl_add_u64 v[248:249], v[248:249], 0, s[26:27]
	v_lshl_add_u64 v[248:249], v[248:249], 0, v[232:233]
	v_lshl_add_u64 v[248:249], v[248:249], 0, s[10:11]
	global_load_ushort v220, v[248:249], off
	global_load_ushort v221, v[248:249], off offset:32
	global_load_ushort v222, v[248:249], off offset:64
	global_load_ushort v223, v[248:249], off offset:96
	v_or_b32_e32 v246, 2, v132
	v_add_u32_e32 v246, s6, v246
	v_mul_u32_u24_e32 v246, 0x1200, v246
	v_lshl_add_u64 v[248:249], s[92:93], 0, v[246:247]
	v_lshl_add_u64 v[248:249], v[248:249], 0, s[26:27]
	v_lshl_add_u64 v[248:249], v[248:249], 0, v[232:233]
	v_lshl_add_u64 v[248:249], v[248:249], 0, s[10:11]
	global_load_ushort v224, v[248:249], off
	global_load_ushort v225, v[248:249], off offset:32
	global_load_ushort v226, v[248:249], off offset:64
	global_load_ushort v227, v[248:249], off offset:96
	v_or_b32_e32 v246, 3, v132
	v_add_u32_e32 v246, s6, v246
	v_mul_u32_u24_e32 v246, 0x1200, v246
	v_lshl_add_u64 v[248:249], s[92:93], 0, v[246:247]
	v_lshl_add_u64 v[248:249], v[248:249], 0, s[26:27]
	v_lshl_add_u64 v[248:249], v[248:249], 0, v[232:233]
	v_lshl_add_u64 v[248:249], v[248:249], 0, s[10:11]
	global_load_ushort v228, v[248:249], off
	global_load_ushort v229, v[248:249], off offset:32
	global_load_ushort v230, v[248:249], off offset:64
	global_load_ushort v231, v[248:249], off offset:96
	s_waitcnt lgkmcnt(0)
	v_mfma_f32_16x16x32_bf16 v[126:129], v[208:211], v[2:5], v[14:17]
	v_mfma_f32_16x16x32_bf16 v[94:97], v[212:215], v[2:5], v[10:13]
	ds_read_b128 v[2:5], v137 offset:18432
	v_mfma_f32_16x16x32_bf16 v[18:21], v[6:9], v[18:21], 0
	s_waitcnt lgkmcnt(0)
	v_mfma_f32_16x16x32_bf16 v[122:125], v[208:211], v[2:5], v[22:25]
	v_mfma_f32_16x16x32_bf16 v[90:93], v[212:215], v[2:5], v[18:21]
	ds_read_b128 v[2:5], v137 offset:20480
	v_mfma_f32_16x16x32_bf16 v[26:29], v[6:9], v[26:29], 0
	s_waitcnt lgkmcnt(0)
	v_mfma_f32_16x16x32_bf16 v[118:121], v[208:211], v[2:5], v[30:33]
	v_mfma_f32_16x16x32_bf16 v[86:89], v[212:215], v[2:5], v[26:29]
	ds_read_b128 v[2:5], v137 offset:22528
	v_mfma_f32_16x16x32_bf16 v[34:37], v[6:9], v[34:37], 0
	s_waitcnt lgkmcnt(0)
	v_mfma_f32_16x16x32_bf16 v[114:117], v[208:211], v[2:5], v[38:41]
	v_mfma_f32_16x16x32_bf16 v[82:85], v[212:215], v[2:5], v[34:37]
	ds_read_b128 v[2:5], v137 offset:24576
	v_mfma_f32_16x16x32_bf16 v[42:45], v[6:9], v[42:45], 0
	s_waitcnt lgkmcnt(0)
	v_mfma_f32_16x16x32_bf16 v[110:113], v[208:211], v[2:5], v[46:49]
	v_mfma_f32_16x16x32_bf16 v[78:81], v[212:215], v[2:5], v[42:45]
	ds_read_b128 v[2:5], v137 offset:26624
	v_mfma_f32_16x16x32_bf16 v[50:53], v[6:9], v[50:53], 0
	v_mfma_f32_16x16x32_bf16 v[200:203], v[6:9], v[74:77], 0
	s_waitcnt lgkmcnt(0)
	v_mfma_f32_16x16x32_bf16 v[106:109], v[208:211], v[2:5], v[54:57]
	v_mfma_f32_16x16x32_bf16 v[74:77], v[212:215], v[2:5], v[50:53]
	ds_read_b128 v[2:5], v137 offset:28672
	v_mfma_f32_16x16x32_bf16 v[58:61], v[6:9], v[58:61], 0
	v_mfma_f32_16x16x32_bf16 v[196:199], v[6:9], v[70:73], 0
	s_waitcnt lgkmcnt(0)
	v_mfma_f32_16x16x32_bf16 v[102:105], v[208:211], v[2:5], v[62:65]
	v_mfma_f32_16x16x32_bf16 v[70:73], v[212:215], v[2:5], v[58:61]
	ds_read_b128 v[2:5], v137 offset:30720
	v_mfma_f32_16x16x32_bf16 v[66:69], v[6:9], v[66:69], 0
	s_waitcnt lgkmcnt(0)
	v_mfma_f32_16x16x32_bf16 v[98:101], v[208:211], v[2:5], v[98:101]
	v_mfma_f32_16x16x32_bf16 v[66:69], v[212:215], v[2:5], v[66:69]
	ds_read_b128 v[2:5], v137 offset:49152
	ds_read_b128 v[6:9], v137 offset:57344
	ds_read_b128 v[10:13], v137 offset:51200
	ds_read_b128 v[14:17], v137 offset:59392
	ds_read_b128 v[18:21], v137 offset:53248
	ds_read_b128 v[22:25], v137 offset:61440
	s_waitcnt lgkmcnt(5)
	v_mfma_f32_16x16x32_bf16 v[34:37], v[208:211], v[2:5], v[138:141]
	ds_read_b128 v[26:29], v137 offset:55296
	s_nop 1
	ds_read_b128 v[138:141], v137 offset:63488
	v_sub_u32_e32 v137, v132, v0
	v_cmp_lt_i32_e32 vcc, -1, v137
	s_waitcnt lgkmcnt(1)
	v_mfma_f32_16x16x32_bf16 v[62:65], v[208:211], v[26:29], v[188:191]
	v_add_u32_e32 v234, 0xffffff81, v175
	v_cvt_f32_u32_e32 v235, v234
	v_cmp_lt_i32_e32 vcc, -1, v234
	v_mul_f32_e32 v235, v235, v131
	v_mul_f32_e32 v235, 0xbfb8aa3b, v235
	v_exp_f32_e32 v235, v235
	s_nop 0
	v_add_f32_e32 v235, 0, v235
	v_cndmask_b32_e32 v236, 0, v235, vcc
	v_cmp_gt_i32_e32 vcc, 1, v234
	v_sub_u32_e32 v237, 0, v234
	v_cvt_f32_u32_e32 v237, v237
	v_mul_f32_e32 v237, v237, v130
	v_mul_f32_e32 v237, 0xbfb8aa3b, v237
	v_exp_f32_e32 v237, v237
	s_nop 0
	v_add_f32_e32 v237, v237, v236
	v_cndmask_b32_e32 v237, v235, v237, vcc
	v_lshlrev_b32_e32 v239, 2, v175
	v_add_u32_e32 v239, 0x10400, v239
	ds_write_b32 v239, v237
	s_waitcnt lgkmcnt(0)
	s_barrier
	v_sub_u32_e32 v242, v132, v0
	v_lshlrev_b32_e32 v242, 2, v242
	v_add_u32_e32 v242, 0x1043c, v242
	ds_read_b32 v234, v242 offset:448
	ds_read_b32 v235, v242 offset:452
	ds_read_b32 v236, v242 offset:456
	v_mfma_f32_16x16x32_bf16 v[58:61], v[208:211], v[138:141], v[192:195]
	s_nop 2
	v_mfma_f32_16x16x32_bf16 v[30:33], v[212:215], v[26:29], v[196:199]
	s_nop 2
	v_mfma_f32_16x16x32_bf16 v[26:29], v[212:215], v[138:141], v[200:203]
	s_nop 2
	v_lshlrev_b32_e32 v140, 7, v132
	v_mfma_f32_16x16x32_bf16 v[2:5], v[212:215], v[2:5], v[146:149]
	s_nop 2
	v_cmp_gt_i32_e32 vcc, 1, v137
	v_mfma_f32_16x16x32_bf16 v[38:41], v[208:211], v[6:9], v[142:145]
	s_nop 2
	v_mfma_f32_16x16x32_bf16 v[6:9], v[212:215], v[6:9], v[150:153]
	s_nop 2
	v_lshlrev_b32_e32 v139, 2, v132
	v_bitop3_b32 v137, v139, 56, v0 bitop3:0xc8
	s_waitcnt lgkmcnt(2)
	ds_read_b32 v237, v242 offset:460
	v_mul_f32_e32 v126, v234, v126
	v_lshl_add_u32 v141, v137, 1, 0
	v_and_b32_e32 v137, 14, v133
	v_cvt_pk_bf16_f32 v126, v126, s0
	v_add3_u32 v146, v141, v140, v137
	v_or_b32_e32 v133, 1, v132
	ds_write_b16 v146, v126
	v_mul_f32_e32 v90, v234, v90
	v_cvt_pk_bf16_f32 v90, v90, s0
	v_mfma_f32_16x16x32_bf16 v[42:45], v[208:211], v[10:13], v[154:157]
	s_nop 2
	v_mfma_f32_16x16x32_bf16 v[46:49], v[208:211], v[14:17], v[158:161]
	s_nop 2
	v_mfma_f32_16x16x32_bf16 v[50:53], v[208:211], v[18:21], v[170:173]
	s_nop 2
	v_lshlrev_b32_e32 v141, 2, v133
	s_waitcnt lgkmcnt(3)
	ds_read_b32 v234, v242 offset:384
	v_mul_f32_e32 v126, v235, v127
	v_bitop3_b32 v127, v141, 56, v0 bitop3:0xc8
	v_lshl_add_u32 v127, v127, 1, 0
	v_lshlrev_b32_e32 v142, 7, v133
	v_cvt_pk_bf16_f32 v126, v126, s0
	v_add3_u32 v147, v127, v142, v137
	v_or_b32_e32 v127, 2, v132
	ds_write_b16 v147, v126
	v_mfma_f32_16x16x32_bf16 v[54:57], v[208:211], v[22:25], v[176:179]
	s_nop 2
	v_mfma_f32_16x16x32_bf16 v[10:13], v[212:215], v[10:13], v[162:165]
	s_nop 2
	v_mfma_f32_16x16x32_bf16 v[14:17], v[212:215], v[14:17], v[166:169]
	s_nop 2
	v_mfma_f32_16x16x32_bf16 v[18:21], v[212:215], v[18:21], v[180:183]
	s_nop 2
	v_lshlrev_b32_e32 v143, 2, v127
	s_waitcnt lgkmcnt(4)
	ds_read_b32 v235, v242 offset:388
	v_mul_f32_e32 v126, v236, v128
	v_bitop3_b32 v128, v143, 56, v0 bitop3:0x48
	v_lshl_add_u32 v128, v128, 1, 0
	v_lshlrev_b32_e32 v144, 7, v127
	v_cvt_pk_bf16_f32 v126, v126, s0
	v_add3_u32 v148, v128, v144, v137
	ds_write_b16 v148, v126
	v_or_b32_e32 v126, 3, v132
	v_mfma_f32_16x16x32_bf16 v[22:25], v[212:215], v[22:25], v[184:187]
	s_nop 2
	s_nop 0
	s_nop 0
	s_waitcnt lgkmcnt(5)
	ds_read_b32 v236, v242 offset:392
	v_mul_f32_e32 v128, v237, v129
	v_lshlrev_b32_e32 v129, 2, v126
	v_bitop3_b32 v145, v129, 56, v0 bitop3:0x48
	v_lshl_add_u32 v149, v145, 1, 0
	v_lshlrev_b32_e32 v145, 7, v126
	v_cvt_pk_bf16_f32 v128, v128, s0
	v_add3_u32 v149, v149, v145, v137
	ds_write_b16 v149, v128
	v_or_b32_e32 v128, 16, v0
	s_nop 0
	s_nop 0
	s_waitcnt lgkmcnt(5)
	ds_read_b32 v237, v242 offset:396
	v_mul_f32_e32 v122, v234, v122
	v_bitop3_b32 v150, v139, 56, v128 bitop3:0x48
	v_lshl_add_u32 v150, v150, 1, 0
	v_cvt_pk_bf16_f32 v122, v122, s0
	v_add3_u32 v150, v150, v140, v137
	ds_write_b16 v150, v122
	s_nop 0
	s_nop 0
	s_waitcnt lgkmcnt(5)
	ds_read_b32 v234, v242 offset:320
	v_mul_f32_e32 v122, v235, v123
	v_bitop3_b32 v123, v141, 56, v128 bitop3:0x48
	v_lshl_add_u32 v123, v123, 1, 0
	v_cvt_pk_bf16_f32 v122, v122, s0
	v_add3_u32 v123, v123, v142, v137
	ds_write_b16 v123, v122
	s_nop 0
	s_nop 0
	v_bitop3_b32 v123, v143, 56, v128 bitop3:0x48
	s_waitcnt lgkmcnt(5)
	ds_read_b32 v235, v242 offset:324
	v_mul_f32_e32 v122, v236, v124
	v_lshl_add_u32 v123, v123, 1, 0
	v_cvt_pk_bf16_f32 v122, v122, s0
	v_add3_u32 v123, v123, v144, v137
	ds_write_b16 v123, v122
	s_nop 0
	s_nop 0
	v_bitop3_b32 v123, v129, 56, v128 bitop3:0x48
	s_waitcnt lgkmcnt(5)
	ds_read_b32 v236, v242 offset:328
	v_mul_f32_e32 v122, v237, v125
	v_lshl_add_u32 v123, v123, 1, 0
	v_cvt_pk_bf16_f32 v122, v122, s0
	v_add3_u32 v123, v123, v145, v137
	ds_write_b16 v123, v122
	v_or_b32_e32 v122, 32, v0
	s_nop 0
	s_nop 0
	s_waitcnt lgkmcnt(5)
	ds_read_b32 v237, v242 offset:332
	v_mul_f32_e32 v118, v234, v118
	v_bitop3_b32 v123, v139, 56, v122 bitop3:0x48
	v_lshl_add_u32 v123, v123, 1, 0
	v_cvt_pk_bf16_f32 v118, v118, s0
	v_add3_u32 v123, v123, v140, v137
	ds_write_b16 v123, v118
	s_nop 0
	s_nop 0
	s_waitcnt lgkmcnt(5)
	ds_read_b32 v234, v242 offset:256
	v_mul_f32_e32 v118, v235, v119
	v_bitop3_b32 v119, v141, 56, v122 bitop3:0x48
	v_lshl_add_u32 v119, v119, 1, 0
	v_cvt_pk_bf16_f32 v118, v118, s0
	v_add3_u32 v119, v119, v142, v137
	ds_write_b16 v119, v118
	v_add3_u32 v124, 0, v136, v134
	v_add_u32_e32 v125, s0, v124
	s_nop 0
	s_nop 0
	v_bitop3_b32 v119, v143, 56, v122 bitop3:0x48
	s_waitcnt lgkmcnt(5)
	ds_read_b32 v235, v242 offset:260
	v_mul_f32_e32 v118, v236, v120
	v_lshl_add_u32 v119, v119, 1, 0
	v_cvt_pk_bf16_f32 v118, v118, s0
	v_add3_u32 v119, v119, v144, v137
	ds_write_b16 v119, v118
	s_nop 0
	s_nop 0
	v_bitop3_b32 v119, v129, 56, v122 bitop3:0x48
	s_waitcnt lgkmcnt(5)
	ds_read_b32 v236, v242 offset:264
	v_mul_f32_e32 v118, v237, v121
	v_lshl_add_u32 v119, v119, 1, 0
	v_cvt_pk_bf16_f32 v118, v118, s0
	v_add3_u32 v119, v119, v145, v137
	ds_write_b16 v119, v118
	v_or_b32_e32 v118, 48, v0
	s_nop 0
	s_nop 0
	s_waitcnt lgkmcnt(5)
	ds_read_b32 v237, v242 offset:268
	v_mul_f32_e32 v114, v234, v114
	v_bitop3_b32 v119, v139, 56, v118 bitop3:0x48
	v_lshl_add_u32 v119, v119, 1, 0
	v_cvt_pk_bf16_f32 v114, v114, s0
	v_add3_u32 v119, v119, v140, v137
	ds_write_b16 v119, v114
	s_nop 0
	s_nop 0
	s_waitcnt lgkmcnt(5)
	ds_read_b32 v234, v242 offset:192
	v_mul_f32_e32 v114, v235, v115
	v_bitop3_b32 v115, v141, 56, v118 bitop3:0x48
	v_lshl_add_u32 v115, v115, 1, 0
	v_cvt_pk_bf16_f32 v114, v114, s0
	v_add3_u32 v115, v115, v142, v137
	ds_write_b16 v115, v114
	s_nop 0
	s_nop 0
	v_bitop3_b32 v115, v143, 56, v118 bitop3:0x48
	s_waitcnt lgkmcnt(5)
	ds_read_b32 v235, v242 offset:196
	v_mul_f32_e32 v114, v236, v116
	v_lshl_add_u32 v115, v115, 1, 0
	v_cvt_pk_bf16_f32 v114, v114, s0
	v_add3_u32 v115, v115, v144, v137
	ds_write_b16 v115, v114
	s_nop 0
	s_nop 0
	v_bitop3_b32 v115, v129, 56, v118 bitop3:0x48
	s_waitcnt lgkmcnt(5)
	ds_read_b32 v236, v242 offset:200
	v_mul_f32_e32 v114, v237, v117
	v_lshl_add_u32 v115, v115, 1, 0
	v_cvt_pk_bf16_f32 v114, v114, s0
	v_add3_u32 v115, v115, v145, v137
	ds_write_b16 v115, v114
	v_or_b32_e32 v114, 64, v0
	s_nop 0
	s_nop 0
	s_waitcnt lgkmcnt(5)
	ds_read_b32 v237, v242 offset:204
	v_mul_f32_e32 v110, v234, v110
	v_cvt_pk_bf16_f32 v110, v110, s0
	ds_write_b16 v146, v110 offset:16384
	s_nop 0
	s_nop 0
	s_waitcnt lgkmcnt(5)
	ds_read_b32 v234, v242 offset:128
	v_mul_f32_e32 v110, v235, v111
	v_cvt_pk_bf16_f32 v110, v110, s0
	ds_write_b16 v147, v110 offset:16384
	s_nop 0
	s_nop 0
	s_waitcnt lgkmcnt(5)
	ds_read_b32 v235, v242 offset:132
	v_mul_f32_e32 v110, v236, v112
	v_cvt_pk_bf16_f32 v110, v110, s0
	ds_write_b16 v148, v110 offset:16384
	v_or_b32_e32 v115, 16, v132
	s_nop 0
	s_nop 0
	s_waitcnt lgkmcnt(5)
	ds_read_b32 v236, v242 offset:136
	v_mul_f32_e32 v110, v237, v113
	v_cvt_pk_bf16_f32 v110, v110, s0
	v_or_b32_e32 v113, 0x50, v0
	ds_write_b16 v149, v110 offset:16384
	s_nop 0
	s_nop 0
	s_waitcnt lgkmcnt(5)
	ds_read_b32 v237, v242 offset:140
	v_mul_f32_e32 v106, v234, v106
	v_bitop3_b32 v110, v139, 56, v113 bitop3:0x48
	v_lshl_add_u32 v110, v110, 1, 0
	v_cvt_pk_bf16_f32 v106, v106, s0
	v_add3_u32 v110, v110, v140, v137
	ds_write_b16 v110, v106 offset:16384
	v_or_b32_e32 v112, 17, v132
	s_nop 0
	s_nop 0
	s_waitcnt lgkmcnt(5)
	ds_read_b32 v234, v242 offset:64
	v_mul_f32_e32 v106, v235, v107
	v_bitop3_b32 v107, v141, 56, v113 bitop3:0x48
	v_lshl_add_u32 v107, v107, 1, 0
	v_cvt_pk_bf16_f32 v106, v106, s0
	v_add3_u32 v107, v107, v142, v137
	ds_write_b16 v107, v106 offset:16384
	v_or_b32_e32 v111, 18, v132
	s_nop 0
	s_nop 0
	v_bitop3_b32 v107, v143, 56, v113 bitop3:0x48
	s_waitcnt lgkmcnt(5)
	ds_read_b32 v235, v242 offset:68
	v_mul_f32_e32 v106, v236, v108
	v_lshl_add_u32 v107, v107, 1, 0
	v_cvt_pk_bf16_f32 v106, v106, s0
	v_add3_u32 v107, v107, v144, v137
	ds_write_b16 v107, v106 offset:16384
	v_or_b32_e32 v110, 19, v132
	s_nop 0
	s_nop 0
	v_bitop3_b32 v107, v129, 56, v113 bitop3:0x48
	s_waitcnt lgkmcnt(5)
	ds_read_b32 v236, v242 offset:72
	v_mul_f32_e32 v106, v237, v109
	v_lshl_add_u32 v107, v107, 1, 0
	v_cvt_pk_bf16_f32 v106, v106, s0
	v_add3_u32 v107, v107, v145, v137
	ds_write_b16 v107, v106 offset:16384
	v_or_b32_e32 v106, 0x60, v0
	s_nop 0
	s_nop 0
	s_waitcnt lgkmcnt(5)
	ds_read_b32 v237, v242 offset:76
	v_mul_f32_e32 v102, v234, v102
	v_bitop3_b32 v107, v139, 56, v106 bitop3:0x48
	v_lshl_add_u32 v107, v107, 1, 0
	v_cvt_pk_bf16_f32 v102, v102, s0
	v_add3_u32 v107, v107, v140, v137
	ds_write_b16 v107, v102 offset:16384
	s_nop 0
	s_nop 0
	s_waitcnt lgkmcnt(5)
	ds_read_b32 v234, v242 offset:0
	v_mul_f32_e32 v102, v235, v103
	v_bitop3_b32 v103, v141, 56, v106 bitop3:0x48
	v_lshl_add_u32 v103, v103, 1, 0
	v_cvt_pk_bf16_f32 v102, v102, s0
	v_add3_u32 v103, v103, v142, v137
	ds_write_b16 v103, v102 offset:16384
	s_nop 0
	s_nop 0
	v_bitop3_b32 v103, v143, 56, v106 bitop3:0x48
	s_waitcnt lgkmcnt(5)
	ds_read_b32 v235, v242 offset:4
	v_mul_f32_e32 v102, v236, v104
	v_lshl_add_u32 v103, v103, 1, 0
	v_cvt_pk_bf16_f32 v102, v102, s0
	v_add3_u32 v103, v103, v144, v137
	ds_write_b16 v103, v102 offset:16384
	s_nop 0
	s_nop 0
	v_bitop3_b32 v103, v129, 56, v106 bitop3:0x48
	s_waitcnt lgkmcnt(5)
	ds_read_b32 v236, v242 offset:8
	v_mul_f32_e32 v102, v237, v105
	v_lshl_add_u32 v103, v103, 1, 0
	v_cvt_pk_bf16_f32 v102, v102, s0
	v_add3_u32 v103, v103, v145, v137
	ds_write_b16 v103, v102 offset:16384
	v_or_b32_e32 v102, 0x70, v0
	s_nop 0
	s_nop 0
	s_waitcnt lgkmcnt(5)
	ds_read_b32 v237, v242 offset:12
	v_mul_f32_e32 v98, v234, v98
	v_bitop3_b32 v103, v139, 56, v102 bitop3:0x48
	v_lshl_add_u32 v103, v103, 1, 0
	v_cvt_pk_bf16_f32 v98, v98, s0
	v_add3_u32 v103, v103, v140, v137
	ds_write_b16 v103, v98 offset:16384
	s_nop 0
	s_nop 0
	s_waitcnt lgkmcnt(5)
	ds_read_b32 v234, v242 offset:512
	v_mul_f32_e32 v98, v235, v99
	v_bitop3_b32 v99, v141, 56, v102 bitop3:0x48
	v_lshl_add_u32 v99, v99, 1, 0
	v_cvt_pk_bf16_f32 v98, v98, s0
	v_add3_u32 v99, v99, v142, v137
	ds_write_b16 v99, v98 offset:16384
	s_nop 0
	s_nop 0
	v_bitop3_b32 v99, v143, 56, v102 bitop3:0x48
	s_waitcnt lgkmcnt(5)
	ds_read_b32 v235, v242 offset:516
	v_mul_f32_e32 v98, v236, v100
	v_lshl_add_u32 v99, v99, 1, 0
	v_cvt_pk_bf16_f32 v98, v98, s0
	v_add3_u32 v99, v99, v144, v137
	ds_write_b16 v99, v98 offset:16384
	s_nop 0
	s_nop 0
	v_bitop3_b32 v99, v129, 56, v102 bitop3:0x48
	s_waitcnt lgkmcnt(5)
	ds_read_b32 v236, v242 offset:520
	v_mul_f32_e32 v98, v237, v101
	v_lshl_add_u32 v99, v99, 1, 0
	v_cvt_pk_bf16_f32 v98, v98, s0
	v_add3_u32 v99, v99, v145, v137
	ds_write_b16 v99, v98 offset:16384
	s_nop 0
	s_nop 0
	s_waitcnt lgkmcnt(5)
	ds_read_b32 v237, v242 offset:524
	v_mul_f32_e32 v94, v234, v94
	v_cvt_pk_bf16_f32 v99, v94, s0
	v_lshlrev_b32_e32 v94, 2, v115
	v_bitop3_b32 v98, v94, 56, v0 bitop3:0xc8
	v_lshl_add_u32 v100, v98, 1, 0
	v_lshlrev_b32_e32 v98, 7, v115
	v_add3_u32 v103, v100, v98, v137
	ds_write_b16 v103, v99
	s_nop 0
	s_nop 0
	s_waitcnt lgkmcnt(5)
	ds_read_b32 v234, v242 offset:452
	v_mul_f32_e32 v95, v235, v95
	v_cvt_pk_bf16_f32 v100, v95, s0
	v_lshlrev_b32_e32 v95, 2, v112
	v_bitop3_b32 v99, v95, 56, v0 bitop3:0xc8
	v_lshl_add_u32 v101, v99, 1, 0
	v_lshlrev_b32_e32 v99, 7, v112
	v_add3_u32 v104, v101, v99, v137
	ds_write_b16 v104, v100
	s_nop 0
	s_nop 0
	s_waitcnt lgkmcnt(5)
	ds_read_b32 v235, v242 offset:456
	v_mul_f32_e32 v96, v236, v96
	v_cvt_pk_bf16_f32 v101, v96, s0
	v_lshlrev_b32_e32 v96, 2, v111
	v_bitop3_b32 v100, v96, 56, v0 bitop3:0x48
	v_lshl_add_u32 v105, v100, 1, 0
	v_lshlrev_b32_e32 v100, 7, v111
	v_add3_u32 v105, v105, v100, v137
	ds_write_b16 v105, v101
	s_nop 0
	s_nop 0
	s_waitcnt lgkmcnt(5)
	ds_read_b32 v236, v242 offset:460
	v_mul_f32_e32 v97, v237, v97
	v_cvt_pk_bf16_f32 v108, v97, s0
	v_lshlrev_b32_e32 v97, 2, v110
	v_bitop3_b32 v101, v97, 56, v0 bitop3:0x48
	v_lshl_add_u32 v107, v101, 1, 0
	v_lshlrev_b32_e32 v101, 7, v110
	v_add3_u32 v107, v107, v101, v137
	ds_write_b16 v107, v108
	v_bitop3_b32 v108, v94, 56, v128 bitop3:0x48
	v_lshl_add_u32 v108, v108, 1, 0
	v_add3_u32 v108, v108, v98, v137
	ds_write_b16 v108, v90
	v_lshlrev_b32_e32 v0, 1, v0
	s_nop 0
	s_nop 0
	s_waitcnt lgkmcnt(6)
	ds_read_b32 v237, v242 offset:384
	v_mul_f32_e32 v90, v234, v91
	v_bitop3_b32 v91, v95, 56, v128 bitop3:0x48
	v_lshl_add_u32 v91, v91, 1, 0
	v_cvt_pk_bf16_f32 v90, v90, s0
	v_add3_u32 v91, v91, v99, v137
	ds_write_b16 v91, v90
	s_nop 0
	s_nop 0
	v_bitop3_b32 v91, v96, 56, v128 bitop3:0x48
	s_waitcnt lgkmcnt(6)
	ds_read_b32 v234, v242 offset:388
	v_mul_f32_e32 v90, v235, v92
	v_lshl_add_u32 v91, v91, 1, 0
	v_cvt_pk_bf16_f32 v90, v90, s0
	v_add3_u32 v91, v91, v100, v137
	ds_write_b16 v91, v90
	s_nop 0
	s_nop 0
	v_bitop3_b32 v91, v97, 56, v128 bitop3:0x48
	s_waitcnt lgkmcnt(6)
	ds_read_b32 v235, v242 offset:392
	v_mul_f32_e32 v90, v236, v93
	v_lshl_add_u32 v91, v91, 1, 0
	v_cvt_pk_bf16_f32 v90, v90, s0
	v_add3_u32 v91, v91, v101, v137
	ds_write_b16 v91, v90
	s_nop 0
	s_nop 0
	s_waitcnt lgkmcnt(5)
	ds_read_b32 v236, v242 offset:396
	v_mul_f32_e32 v86, v237, v86
	v_bitop3_b32 v90, v94, 56, v122 bitop3:0x48
	v_lshl_add_u32 v90, v90, 1, 0
	v_cvt_pk_bf16_f32 v86, v86, s0
	v_add3_u32 v90, v90, v98, v137
	ds_write_b16 v90, v86
	s_nop 0
	s_nop 0
	s_waitcnt lgkmcnt(5)
	ds_read_b32 v237, v242 offset:320
	v_mul_f32_e32 v86, v234, v87
	v_bitop3_b32 v87, v95, 56, v122 bitop3:0x48
	v_lshl_add_u32 v87, v87, 1, 0
	v_cvt_pk_bf16_f32 v86, v86, s0
	v_add3_u32 v87, v87, v99, v137
	ds_write_b16 v87, v86
	s_nop 0
	s_nop 0
	v_bitop3_b32 v87, v96, 56, v122 bitop3:0x48
	s_waitcnt lgkmcnt(5)
	ds_read_b32 v234, v242 offset:324
	v_mul_f32_e32 v86, v235, v88
	v_lshl_add_u32 v87, v87, 1, 0
	v_cvt_pk_bf16_f32 v86, v86, s0
	v_add3_u32 v87, v87, v100, v137
	ds_write_b16 v87, v86
	s_nop 0
	s_nop 0
	v_bitop3_b32 v87, v97, 56, v122 bitop3:0x48
	s_waitcnt lgkmcnt(5)
	ds_read_b32 v235, v242 offset:328
	v_mul_f32_e32 v86, v236, v89
	v_lshl_add_u32 v87, v87, 1, 0
	v_cvt_pk_bf16_f32 v86, v86, s0
	v_add3_u32 v87, v87, v101, v137
	ds_write_b16 v87, v86
	s_nop 0
	s_nop 0
	s_waitcnt lgkmcnt(5)
	ds_read_b32 v236, v242 offset:332
	v_mul_f32_e32 v82, v237, v82
	v_bitop3_b32 v86, v94, 56, v118 bitop3:0x48
	v_lshl_add_u32 v86, v86, 1, 0
	v_cvt_pk_bf16_f32 v82, v82, s0
	v_add3_u32 v86, v86, v98, v137
	ds_write_b16 v86, v82
	s_nop 0
	s_nop 0
	s_waitcnt lgkmcnt(5)
	ds_read_b32 v237, v242 offset:256
	v_mul_f32_e32 v82, v234, v83
	v_bitop3_b32 v83, v95, 56, v118 bitop3:0x48
	v_lshl_add_u32 v83, v83, 1, 0
	v_cvt_pk_bf16_f32 v82, v82, s0
	v_add3_u32 v83, v83, v99, v137
	ds_write_b16 v83, v82
	s_nop 0
	s_nop 0
	v_bitop3_b32 v83, v96, 56, v118 bitop3:0x48
	s_waitcnt lgkmcnt(5)
	ds_read_b32 v234, v242 offset:260
	v_mul_f32_e32 v82, v235, v84
	v_lshl_add_u32 v83, v83, 1, 0
	v_cvt_pk_bf16_f32 v82, v82, s0
	v_add3_u32 v83, v83, v100, v137
	ds_write_b16 v83, v82
	s_nop 0
	s_nop 0
	v_bitop3_b32 v83, v97, 56, v118 bitop3:0x48
	s_waitcnt lgkmcnt(5)
	ds_read_b32 v235, v242 offset:264
	v_mul_f32_e32 v82, v236, v85
	v_lshl_add_u32 v83, v83, 1, 0
	v_cvt_pk_bf16_f32 v82, v82, s0
	v_add3_u32 v83, v83, v101, v137
	ds_write_b16 v83, v82
	s_nop 0
	s_nop 0
	s_waitcnt lgkmcnt(5)
	ds_read_b32 v236, v242 offset:268
	v_mul_f32_e32 v78, v237, v78
	v_cvt_pk_bf16_f32 v78, v78, s0
	ds_write_b16 v103, v78 offset:16384
	s_nop 0
	s_nop 0
	s_waitcnt lgkmcnt(5)
	ds_read_b32 v237, v242 offset:192
	v_mul_f32_e32 v78, v234, v79
	v_cvt_pk_bf16_f32 v78, v78, s0
	ds_write_b16 v104, v78 offset:16384
	s_nop 0
	s_nop 0
	s_waitcnt lgkmcnt(5)
	ds_read_b32 v234, v242 offset:196
	v_mul_f32_e32 v78, v235, v80
	v_cvt_pk_bf16_f32 v78, v78, s0
	ds_write_b16 v105, v78 offset:16384
	s_nop 0
	s_nop 0
	s_waitcnt lgkmcnt(5)
	ds_read_b32 v235, v242 offset:200
	v_mul_f32_e32 v78, v236, v81
	v_cvt_pk_bf16_f32 v78, v78, s0
	ds_write_b16 v107, v78 offset:16384
	s_nop 0
	s_nop 0
	s_waitcnt lgkmcnt(5)
	ds_read_b32 v236, v242 offset:204
	v_mul_f32_e32 v74, v237, v74
	v_bitop3_b32 v78, v94, 56, v113 bitop3:0x48
	v_lshl_add_u32 v78, v78, 1, 0
	v_cvt_pk_bf16_f32 v74, v74, s0
	v_add3_u32 v78, v78, v98, v137
	ds_write_b16 v78, v74 offset:16384
	s_nop 0
	s_nop 0
	s_waitcnt lgkmcnt(5)
	ds_read_b32 v237, v242 offset:128
	v_mul_f32_e32 v74, v234, v75
	v_bitop3_b32 v75, v95, 56, v113 bitop3:0x48
	v_lshl_add_u32 v75, v75, 1, 0
	v_cvt_pk_bf16_f32 v74, v74, s0
	v_add3_u32 v75, v75, v99, v137
	ds_write_b16 v75, v74 offset:16384
	s_nop 0
	s_nop 0
	v_bitop3_b32 v75, v96, 56, v113 bitop3:0x48
	s_waitcnt lgkmcnt(5)
	ds_read_b32 v234, v242 offset:132
	v_mul_f32_e32 v74, v235, v76
	v_lshl_add_u32 v75, v75, 1, 0
	v_cvt_pk_bf16_f32 v74, v74, s0
	v_add3_u32 v75, v75, v100, v137
	ds_write_b16 v75, v74 offset:16384
	s_nop 0
	s_nop 0
	v_bitop3_b32 v75, v97, 56, v113 bitop3:0x48
	s_waitcnt lgkmcnt(5)
	ds_read_b32 v235, v242 offset:136
	v_mul_f32_e32 v74, v236, v77
	v_lshl_add_u32 v75, v75, 1, 0
	v_cvt_pk_bf16_f32 v74, v74, s0
	v_add3_u32 v75, v75, v101, v137
	ds_write_b16 v75, v74 offset:16384
	v_add3_u32 v113, 0, v135, v134
	v_add_u32_e32 v114, s0, v113
	s_nop 0
	s_nop 0
	s_waitcnt lgkmcnt(5)
	ds_read_b32 v236, v242 offset:140
	v_mul_f32_e32 v70, v237, v70
	v_bitop3_b32 v74, v94, 56, v106 bitop3:0x48
	v_lshl_add_u32 v74, v74, 1, 0
	v_cvt_pk_bf16_f32 v70, v70, s0
	v_add3_u32 v74, v74, v98, v137
	ds_write_b16 v74, v70 offset:16384
	s_nop 0
	s_nop 0
	s_waitcnt lgkmcnt(5)
	ds_read_b32 v237, v242 offset:64
	v_mul_f32_e32 v70, v234, v71
	v_bitop3_b32 v71, v95, 56, v106 bitop3:0x48
	v_lshl_add_u32 v71, v71, 1, 0
	v_cvt_pk_bf16_f32 v70, v70, s0
	v_add3_u32 v71, v71, v99, v137
	ds_write_b16 v71, v70 offset:16384
	s_nop 0
	s_nop 0
	v_bitop3_b32 v71, v96, 56, v106 bitop3:0x48
	s_waitcnt lgkmcnt(5)
	ds_read_b32 v234, v242 offset:68
	v_mul_f32_e32 v70, v235, v72
	v_lshl_add_u32 v71, v71, 1, 0
	v_cvt_pk_bf16_f32 v70, v70, s0
	v_add3_u32 v71, v71, v100, v137
	ds_write_b16 v71, v70 offset:16384
	s_nop 0
	s_nop 0
	v_bitop3_b32 v71, v97, 56, v106 bitop3:0x48
	s_waitcnt lgkmcnt(5)
	ds_read_b32 v235, v242 offset:72
	v_mul_f32_e32 v70, v236, v73
	v_lshl_add_u32 v71, v71, 1, 0
	v_cvt_pk_bf16_f32 v70, v70, s0
	v_add3_u32 v71, v71, v101, v137
	ds_write_b16 v71, v70 offset:16384
	s_nop 0
	s_nop 0
	s_waitcnt lgkmcnt(5)
	ds_read_b32 v236, v242 offset:76
	v_mul_f32_e32 v66, v237, v66
	v_bitop3_b32 v70, v94, 56, v102 bitop3:0x48
	v_lshl_add_u32 v70, v70, 1, 0
	v_cvt_pk_bf16_f32 v66, v66, s0
	v_add3_u32 v70, v70, v98, v137
	ds_write_b16 v70, v66 offset:16384
	s_nop 0
	s_nop 0
	s_waitcnt lgkmcnt(5)
	v_mul_f32_e32 v66, v234, v67
	v_bitop3_b32 v67, v95, 56, v102 bitop3:0x48
	v_lshl_add_u32 v67, v67, 1, 0
	v_cvt_pk_bf16_f32 v66, v66, s0
	v_add3_u32 v67, v67, v99, v137
	ds_write_b16 v67, v66 offset:16384
	s_nop 0
	s_nop 0
	v_bitop3_b32 v67, v96, 56, v102 bitop3:0x48
	s_waitcnt lgkmcnt(4)
	v_mul_f32_e32 v66, v235, v68
	v_lshl_add_u32 v67, v67, 1, 0
	v_cvt_pk_bf16_f32 v66, v66, s0
	v_add3_u32 v67, v67, v100, v137
	ds_write_b16 v67, v66 offset:16384
	s_nop 0
	s_nop 0
	v_bitop3_b32 v67, v97, 56, v102 bitop3:0x48
	s_waitcnt lgkmcnt(3)
	v_mul_f32_e32 v66, v236, v69
	v_lshl_add_u32 v67, v67, 1, 0
	v_cvt_pk_bf16_f32 v66, v66, s0
	v_add3_u32 v67, v67, v101, v137
	ds_write_b16 v67, v66 offset:16384
	s_waitcnt lgkmcnt(0)
	s_barrier
	v_and_b32_e32 v232, 15, v207
	v_lshlrev_b32_e32 v232, 1, v232
	v_mov_b32_e32 v233, 0
	v_mov_b32_e32 v247, 0
	v_or_b32_e32 v246, 16, v132
	v_add_u32_e32 v246, s6, v246
	v_mul_u32_u24_e32 v246, 0x1200, v246
	v_lshl_add_u64 v[248:249], s[92:93], 0, v[246:247]
	v_lshl_add_u64 v[248:249], v[248:249], 0, s[26:27]
	v_lshl_add_u64 v[248:249], v[248:249], 0, v[232:233]
	v_lshl_add_u64 v[248:249], v[248:249], 0, s[10:11]
	global_load_ushort v176, v[248:249], off
	global_load_ushort v177, v[248:249], off offset:32
	global_load_ushort v178, v[248:249], off offset:64
	global_load_ushort v179, v[248:249], off offset:96
	v_or_b32_e32 v246, 17, v132
	v_add_u32_e32 v246, s6, v246
	v_mul_u32_u24_e32 v246, 0x1200, v246
	v_lshl_add_u64 v[248:249], s[92:93], 0, v[246:247]
	v_lshl_add_u64 v[248:249], v[248:249], 0, s[26:27]
	v_lshl_add_u64 v[248:249], v[248:249], 0, v[232:233]
	v_lshl_add_u64 v[248:249], v[248:249], 0, s[10:11]
	global_load_ushort v180, v[248:249], off
	global_load_ushort v181, v[248:249], off offset:32
	global_load_ushort v182, v[248:249], off offset:64
	global_load_ushort v183, v[248:249], off offset:96
	v_or_b32_e32 v246, 18, v132
	v_add_u32_e32 v246, s6, v246
	v_mul_u32_u24_e32 v246, 0x1200, v246
	v_lshl_add_u64 v[248:249], s[92:93], 0, v[246:247]
	v_lshl_add_u64 v[248:249], v[248:249], 0, s[26:27]
	v_lshl_add_u64 v[248:249], v[248:249], 0, v[232:233]
	v_lshl_add_u64 v[248:249], v[248:249], 0, s[10:11]
	global_load_ushort v184, v[248:249], off
	global_load_ushort v185, v[248:249], off offset:32
	global_load_ushort v186, v[248:249], off offset:64
	global_load_ushort v187, v[248:249], off offset:96
	v_or_b32_e32 v246, 19, v132
	v_add_u32_e32 v246, s6, v246
	v_mul_u32_u24_e32 v246, 0x1200, v246
	v_lshl_add_u64 v[248:249], s[92:93], 0, v[246:247]
	v_lshl_add_u64 v[248:249], v[248:249], 0, s[26:27]
	v_lshl_add_u64 v[248:249], v[248:249], 0, v[232:233]
	v_lshl_add_u64 v[248:249], v[248:249], 0, s[10:11]
	global_load_ushort v188, v[248:249], off
	global_load_ushort v189, v[248:249], off offset:32
	global_load_ushort v190, v[248:249], off offset:64
	global_load_ushort v191, v[248:249], off offset:96
	ds_read_b128 v[66:69], v114
	ds_read_b128 v[70:73], v114 offset:2048
	ds_read_b128 v[74:77], v113 offset:32768
	ds_read_b128 v[82:85], v113 offset:34816
	ds_read_b128 v[90:93], v113 offset:36864
	ds_read_b128 v[98:101], v113 offset:38912
	s_waitcnt lgkmcnt(3)
	v_mfma_f32_16x16x32_bf16 v[78:81], v[66:69], v[74:77], 0
	v_readlane_b32 s0, v250, 14
	s_add_u32 s4, s0, s26
	v_readlane_b32 s0, v250, 15
	v_mfma_f32_16x16x32_bf16 v[74:77], v[70:73], v[74:77], 0
	s_addc_u32 s5, s0, 0
	s_waitcnt lgkmcnt(2)
	v_mfma_f32_16x16x32_bf16 v[86:89], v[66:69], v[82:85], 0
	v_mfma_f32_16x16x32_bf16 v[82:85], v[70:73], v[82:85], 0
	s_waitcnt lgkmcnt(1)
	v_mfma_f32_16x16x32_bf16 v[94:97], v[66:69], v[90:93], 0
	v_mfma_f32_16x16x32_bf16 v[90:93], v[70:73], v[90:93], 0
	s_waitcnt lgkmcnt(0)
	v_mfma_f32_16x16x32_bf16 v[66:69], v[66:69], v[98:101], 0
	v_mfma_f32_16x16x32_bf16 v[70:73], v[70:73], v[98:101], 0
	ds_read_b128 v[98:101], v125
	ds_read_b128 v[102:105], v125 offset:2048
	ds_read_b128 v[106:109], v124 offset:32768
	s_waitcnt lgkmcnt(0)
	v_mfma_f32_16x16x32_bf16 v[78:81], v[98:101], v[106:109], v[78:81]
	v_mfma_f32_16x16x32_bf16 v[74:77], v[102:105], v[106:109], v[74:77]
	ds_read_b128 v[106:109], v124 offset:34816
	s_waitcnt lgkmcnt(0)
	v_mfma_f32_16x16x32_bf16 v[86:89], v[98:101], v[106:109], v[86:89]
	v_mfma_f32_16x16x32_bf16 v[82:85], v[102:105], v[106:109], v[82:85]
	ds_read_b128 v[106:109], v124 offset:36864
	s_waitcnt lgkmcnt(0)
	v_mfma_f32_16x16x32_bf16 v[94:97], v[98:101], v[106:109], v[94:97]
	v_mfma_f32_16x16x32_bf16 v[90:93], v[102:105], v[106:109], v[90:93]
	ds_read_b128 v[106:109], v124 offset:38912
	s_waitcnt lgkmcnt(0)
	v_mfma_f32_16x16x32_bf16 v[66:69], v[98:101], v[106:109], v[66:69]
	v_mfma_f32_16x16x32_bf16 v[70:73], v[102:105], v[106:109], v[70:73]
	ds_read_b128 v[98:101], v114 offset:16384
	ds_read_b128 v[102:105], v114 offset:18432
	ds_read_b128 v[106:109], v113 offset:40960
	s_waitcnt lgkmcnt(0)
	v_mfma_f32_16x16x32_bf16 v[78:81], v[98:101], v[106:109], v[78:81]
	v_mfma_f32_16x16x32_bf16 v[74:77], v[102:105], v[106:109], v[74:77]
	ds_read_b128 v[106:109], v113 offset:43008
	s_waitcnt lgkmcnt(0)
	v_mfma_f32_16x16x32_bf16 v[86:89], v[98:101], v[106:109], v[86:89]
	v_mfma_f32_16x16x32_bf16 v[106:109], v[102:105], v[106:109], v[82:85]
	s_nop 2
	ds_read_b128 v[82:85], v113 offset:45056
	s_waitcnt lgkmcnt(0)
	v_mfma_f32_16x16x32_bf16 v[116:119], v[98:101], v[82:85], v[94:97]
	v_mfma_f32_16x16x32_bf16 v[120:123], v[102:105], v[82:85], v[90:93]
	ds_read_b128 v[82:85], v113 offset:47104
	s_waitcnt lgkmcnt(0)
	v_mfma_f32_16x16x32_bf16 v[98:101], v[98:101], v[82:85], v[66:69]
	v_mfma_f32_16x16x32_bf16 v[70:73], v[102:105], v[82:85], v[70:73]
	ds_read_b128 v[102:105], v125 offset:16384
	ds_read_b128 v[134:137], v125 offset:18432
	ds_read_b128 v[66:69], v124 offset:40960
	s_waitcnt lgkmcnt(0)
	v_mfma_f32_16x16x32_bf16 v[82:85], v[102:105], v[66:69], v[78:81]
	v_mfma_f32_16x16x32_bf16 v[66:69], v[134:137], v[66:69], v[74:77]
	s_nop 2
	ds_read_b128 v[74:77], v124 offset:43008
	s_waitcnt lgkmcnt(0)
	v_mfma_f32_16x16x32_bf16 v[78:81], v[134:137], v[74:77], v[106:109]
	s_nop 2
	ds_read_b128 v[106:109], v124 offset:47104
	v_mfma_f32_16x16x32_bf16 v[94:97], v[102:105], v[74:77], v[86:89]
	ds_read_b128 v[74:77], v124 offset:45056
	s_waitcnt lgkmcnt(1)
	v_mfma_f32_16x16x32_bf16 v[86:89], v[102:105], v[106:109], v[98:101]
	s_nop 2
	v_and_b32_e32 v99, 64, v207
	v_xor_b32_e32 v98, 1, v207
	v_add_u32_e32 v99, 64, v99
	v_cmp_lt_i32_e32 vcc, v98, v99
	s_waitcnt lgkmcnt(0)
	v_mfma_f32_16x16x32_bf16 v[90:93], v[102:105], v[74:77], v[116:119]
	v_mov_b32_e32 v100, v38
	v_cndmask_b32_e32 v98, v207, v98, vcc
	v_mov_b32_e32 v101, v34
	v_lshlrev_b32_e32 v117, 2, v98
	v_xor_b32_e32 v98, 2, v207
	v_cmp_lt_i32_e32 vcc, v98, v99
	v_mov_b32_e32 v102, v46
	v_mov_b32_e32 v103, v42
	v_cndmask_b32_e32 v98, v207, v98, vcc
	v_lshlrev_b32_e32 v116, 2, v98
	v_xor_b32_e32 v98, 4, v207
	v_cmp_lt_i32_e32 vcc, v98, v99
	v_mfma_f32_16x16x32_bf16 v[70:73], v[134:137], v[106:109], v[70:73]
	v_mov_b32_e32 v107, v62
	v_cndmask_b32_e32 v98, v207, v98, vcc
	v_lshlrev_b32_e32 v114, 2, v98
	v_xor_b32_e32 v98, 8, v207
	v_cmp_lt_i32_e32 vcc, v98, v99
	v_mov_b32_e32 v105, v86
	v_mfma_f32_16x16x32_bf16 v[74:77], v[134:137], v[74:77], v[120:123]
	v_cndmask_b32_e32 v98, v207, v98, vcc
	v_lshlrev_b32_e32 v113, 2, v98
	v_cvt_f32_i32_e32 v98, v133
	v_mul_f32_e32 v98, v98, v131
	v_mul_f32_e32 v98, 0xbfb8aa3b, v98
	v_exp_f32_e32 v99, v98
	v_sub_u32_e32 v98, 0x80, v132
	v_cvt_f32_i32_e32 v98, v98
	v_mul_f32_e32 v98, v98, v130
	v_mul_f32_e32 v98, 0xbfb8aa3b, v98
	v_exp_f32_e32 v98, v98
	s_nop 0
	v_pk_mul_f32 v[100:101], v[98:99], v[100:101]
	s_nop 0
	v_add_f32_e32 v34, v101, v82
	v_pk_mul_f32 v[102:103], v[98:99], v[102:103]
	v_add_f32_e32 v100, v100, v34
	v_add_f32_e32 v34, v103, v94
	v_add_f32_e32 v46, v102, v34
	v_mov_b32_e32 v102, v54
	v_mov_b32_e32 v103, v50
	v_pk_mul_f32 v[102:103], v[98:99], v[102:103]
	v_mul_f32_e32 v104, v46, v46
	v_add_f32_e32 v34, v103, v90
	v_add_f32_e32 v102, v102, v34
	v_mov_b32_e32 v101, v99
	v_mov_b32_e32 v106, v100
	v_pk_fma_f32 v[104:105], v[100:101], v[106:107], v[104:105]
	v_mov_b32_e32 v103, v98
	v_mov_b32_e32 v98, v102
	v_mov_b32_e32 v99, v58
	v_pk_fma_f32 v[104:105], v[102:103], v[98:99], v[104:105]
	v_add_u32_e32 v106, s6, v132
	v_mov_b64_e32 v[98:99], s[92:93]
	v_mad_i64_i32 v[108:109], s[0:1], v106, s3, v[98:99]
	v_lshl_add_u64 v[108:109], v[108:109], 0, s[26:27]
	v_lshl_add_u64 v[118:119], v[108:109], 0, v[0:1]
	v_lshl_add_u64 v[108:109], v[118:119], 0, s[10:11]
	v_add_co_u32_e32 v118, vcc, s7, v118
	v_ashrrev_i32_e32 v107, 31, v106
	s_nop 0
	v_addc_co_u32_e32 v119, vcc, 0, v119, vcc
	v_lshlrev_b64 v[106:107], 11, v[106:107]
	v_lshl_add_u64 v[106:107], s[4:5], 0, v[106:107]
	v_lshl_add_u64 v[106:107], v[106:107], 0, v[0:1]
	s_waitcnt vmcnt(16)
	v_lshlrev_b32_e32 v34, 16, v216
	v_mul_f32_e32 v38, 0xbfb8aa3b, v34
	v_exp_f32_e32 v38, v38
	s_nop 0
	v_add_f32_e32 v38, 1.0, v38
	v_div_scale_f32 v42, s[0:1], v38, v38, v34
	v_rcp_f32_e32 v50, v42
	s_nop 0
	v_fma_f32 v54, -v42, v50, 1.0
	v_fmac_f32_e32 v50, v54, v50
	v_div_scale_f32 v54, vcc, v34, v38, v34
	v_mul_f32_e32 v58, v54, v50
	v_fma_f32 v62, -v42, v58, v54
	v_fmac_f32_e32 v58, v62, v50
	v_fma_f32 v42, -v42, v58, v54
	v_div_fmas_f32 v42, v42, v50, v58
	v_div_fixup_f32 v82, v42, v38, v34
	s_nop 0
	v_lshlrev_b32_e32 v34, 16, v217
	v_mul_f32_e32 v38, 0xbfb8aa3b, v34
	v_exp_f32_e32 v38, v38
	s_nop 0
	v_add_f32_e32 v38, 1.0, v38
	v_div_scale_f32 v42, s[0:1], v38, v38, v34
	v_rcp_f32_e32 v50, v42
	s_nop 0
	v_fma_f32 v54, -v42, v50, 1.0
	v_fmac_f32_e32 v50, v54, v50
	v_div_scale_f32 v54, vcc, v34, v38, v34
	v_mul_f32_e32 v58, v54, v50
	v_fma_f32 v62, -v42, v58, v54
	v_fmac_f32_e32 v58, v62, v50
	v_fma_f32 v42, -v42, v58, v54
	v_div_fmas_f32 v42, v42, v50, v58
	v_div_fixup_f32 v90, v42, v38, v34
	s_nop 0
	v_lshlrev_b32_e32 v34, 16, v218
	v_mul_f32_e32 v38, 0xbfb8aa3b, v34
	v_exp_f32_e32 v38, v38
	s_nop 0
	v_add_f32_e32 v38, 1.0, v38
	v_div_scale_f32 v42, s[0:1], v38, v38, v34
	v_rcp_f32_e32 v50, v42
	s_nop 0
	v_fma_f32 v54, -v42, v50, 1.0
	v_fmac_f32_e32 v50, v54, v50
	v_div_scale_f32 v54, vcc, v34, v38, v34
	v_mul_f32_e32 v58, v54, v50
	v_fma_f32 v62, -v42, v58, v54
	v_fmac_f32_e32 v58, v62, v50
	v_fma_f32 v42, -v42, v58, v54
	v_div_fmas_f32 v42, v42, v50, v58
	v_div_fixup_f32 v94, v42, v38, v34
	s_nop 0
	v_lshlrev_b32_e32 v34, 16, v219
	v_mul_f32_e32 v38, 0xbfb8aa3b, v34
	v_exp_f32_e32 v38, v38
	s_nop 0
	v_add_f32_e32 v38, 1.0, v38
	v_div_scale_f32 v42, s[0:1], v38, v38, v34
	v_rcp_f32_e32 v50, v42
	s_mov_b32 s0, 0x358637bd
	v_fma_f32 v54, -v42, v50, 1.0
	v_fmac_f32_e32 v50, v54, v50
	v_div_scale_f32 v54, vcc, v34, v38, v34
	v_mul_f32_e32 v58, v54, v50
	v_fma_f32 v62, -v42, v58, v54
	v_fmac_f32_e32 v58, v62, v50
	v_fma_f32 v42, -v42, v58, v54
	v_div_fmas_f32 v42, v42, v50, v58
	v_div_fixup_f32 v101, v42, v38, v34
	v_cvt_f32_i32_e32 v34, v127
	v_mov_b32_e32 v42, v47
	v_mov_b32_e32 v50, v55
	v_mul_f32_e32 v34, v34, v131
	v_mul_f32_e32 v34, 0xbfb8aa3b, v34
	v_exp_f32_e32 v109, v34
	v_sub_u32_e32 v34, 0x80, v133
	v_cvt_f32_i32_e32 v34, v34
	v_mov_b32_e32 v55, v109
	v_mul_f32_e32 v34, v34, v130
	v_mul_f32_e32 v34, 0xbfb8aa3b, v34
	v_exp_f32_e32 v108, v34
	v_mov_b32_e32 v34, v39
	v_pk_mul_f32 v[34:35], v[108:109], v[34:35]
	s_nop 0
	v_add_f32_e32 v35, v35, v83
	v_add_f32_e32 v54, v34, v35
	v_pk_mul_f32 v[34:35], v[108:109], v[42:43]
	v_mov_b32_e32 v62, v54
	v_add_f32_e32 v35, v35, v95
	v_add_f32_e32 v83, v34, v35
	v_pk_mul_f32 v[34:35], v[108:109], v[50:51]
	v_mul_f32_e32 v86, v83, v83
	v_add_f32_e32 v35, v35, v91
	v_add_f32_e32 v42, v34, v35
	v_pk_fma_f32 v[34:35], v[54:55], v[62:63], v[86:87]
	v_mov_b32_e32 v43, v108
	v_mov_b32_e32 v58, v42
	v_pk_fma_f32 v[38:39], v[42:43], v[58:59], v[34:35]
	v_mov_b32_e32 v35, v105
	v_mov_b32_e32 v34, v39
	v_mov_b32_e32 v50, v38
	v_mov_b32_e32 v51, v104
	v_pk_fma_f32 v[34:35], v[34:35], v[34:35], v[50:51]
	s_nop 1
	v_add_f32_dpp v34, v34, v34 quad_perm:[1,0,3,2] row_mask:0xf bank_mask:0xf
	v_add_f32_dpp v35, v35, v35 quad_perm:[1,0,3,2] row_mask:0xf bank_mask:0xf
	s_nop 0
	v_add_f32_dpp v34, v34, v34 quad_perm:[2,3,0,1] row_mask:0xf bank_mask:0xf
	v_add_f32_dpp v35, v35, v35 quad_perm:[2,3,0,1] row_mask:0xf bank_mask:0xf
	s_nop 0
	v_add_f32_dpp v34, v34, v34 row_half_mirror row_mask:0xf bank_mask:0xf
	v_add_f32_dpp v35, v35, v35 row_half_mirror row_mask:0xf bank_mask:0xf
	s_nop 0
	v_add_f32_dpp v34, v34, v34 row_mirror row_mask:0xf bank_mask:0xf
	v_add_f32_dpp v35, v35, v35 row_mirror row_mask:0xf bank_mask:0xf
	s_nop 0
	v_mov_b32_e32 v50, v34
	v_mov_b32_e32 v51, v35
	v_mov_b64_e32 v[34:35], s[0:1]
	v_pk_fma_f32 v[50:51], v[50:51], s[12:13], v[34:35] op_sel_hi:[1,0,0]
	s_nop 0
	v_mul_f32_e32 v38, 0x4b800000, v51
	v_cmp_gt_f32_e64 s[0:1], s8, v51
	v_cmp_gt_f32_e32 vcc, s8, v50
	s_nop 0
	v_cndmask_b32_e64 v38, v51, v38, s[0:1]
	v_rsq_f32_e32 v38, v38
	s_nop 0
	v_mul_f32_e32 v43, 0x45800000, v38
	v_cndmask_b32_e64 v38, v38, v43, s[0:1]
	v_mul_f32_e32 v43, v100, v38
	v_mul_f32_e32 v43, v82, v43
	v_cvt_pk_bf16_f32 v43, v43, s0
	global_store_short v[106:107], v43, off
	v_mul_f32_e32 v43, v46, v38
	v_mul_f32_e32 v43, v43, v90
	v_cvt_pk_bf16_f32 v43, v43, s0
	global_store_short v[106:107], v43, off offset:32
	v_mul_f32_e32 v43, v102, v38
	v_mul_f32_e32 v38, v105, v38
	v_mul_f32_e32 v38, v38, v101
	v_cvt_pk_bf16_f32 v38, v38, s0
	global_store_short v[106:107], v38, off offset:96
	v_mul_f32_e32 v38, 0x4b800000, v50
	v_cndmask_b32_e32 v38, v50, v38, vcc
	v_rsq_f32_e32 v38, v38
	v_mul_f32_e32 v43, v43, v94
	v_add_u32_e32 v46, s6, v133
	v_cvt_pk_bf16_f32 v43, v43, s0
	v_mad_i64_i32 v[50:51], s[0:1], v46, s3, v[98:99]
	v_ashrrev_i32_e32 v47, 31, v46
	v_lshl_add_u64 v[50:51], v[50:51], 0, s[26:27]
	global_store_short v[106:107], v43, off offset:64
	v_mul_f32_e32 v43, 0x45800000, v38
	v_lshlrev_b64 v[46:47], 11, v[46:47]
	v_lshl_add_u64 v[50:51], v[50:51], 0, v[0:1]
	v_cndmask_b32_e32 v38, v38, v43, vcc
	v_lshl_add_u64 v[58:59], s[4:5], 0, v[46:47]
	v_lshl_add_u64 v[46:47], v[50:51], 0, s[10:11]
	v_add_co_u32_e32 v50, vcc, s7, v50
	v_mul_f32_e32 v42, v42, v38
	s_nop 0
	v_addc_co_u32_e32 v51, vcc, 0, v51, vcc
	v_mul_f32_e32 v50, v54, v38
	s_nop 0
	v_lshlrev_b32_e32 v43, 16, v220
	v_mul_f32_e32 v51, 0xbfb8aa3b, v43
	v_exp_f32_e32 v51, v51
	s_nop 0
	v_add_f32_e32 v51, 1.0, v51
	v_div_scale_f32 v54, s[0:1], v51, v51, v43
	v_rcp_f32_e32 v55, v54
	s_nop 0
	v_fma_f32 v62, -v54, v55, 1.0
	v_fmac_f32_e32 v55, v62, v55
	v_div_scale_f32 v62, vcc, v43, v51, v43
	v_mul_f32_e32 v63, v62, v55
	v_fma_f32 v82, -v54, v63, v62
	v_fmac_f32_e32 v63, v82, v55
	v_fma_f32 v54, -v54, v63, v62
	v_div_fmas_f32 v54, v54, v55, v63
	v_div_fixup_f32 v43, v54, v51, v43
	v_mul_f32_e32 v43, v43, v50
	v_cvt_pk_bf16_f32 v43, v43, s0
	v_lshl_add_u64 v[50:51], v[58:59], 0, v[0:1]
	global_store_short v[50:51], v43, off
	v_mul_f32_e32 v54, v83, v38
	v_mul_f32_e32 v38, v39, v38
	s_nop 0
	v_lshlrev_b32_e32 v43, 16, v221
	v_mul_f32_e32 v55, 0xbfb8aa3b, v43
	v_exp_f32_e32 v55, v55
	s_nop 0
	v_add_f32_e32 v55, 1.0, v55
	v_div_scale_f32 v58, s[0:1], v55, v55, v43
	v_rcp_f32_e32 v59, v58
	s_nop 0
	v_fma_f32 v62, -v58, v59, 1.0
	v_fmac_f32_e32 v59, v62, v59
	v_div_scale_f32 v62, vcc, v43, v55, v43
	v_mul_f32_e32 v63, v62, v59
	v_fma_f32 v82, -v58, v63, v62
	v_fmac_f32_e32 v63, v82, v59
	v_fma_f32 v58, -v58, v63, v62
	v_div_fmas_f32 v58, v58, v59, v63
	v_div_fixup_f32 v43, v58, v55, v43
	v_mul_f32_e32 v43, v54, v43
	v_cvt_pk_bf16_f32 v43, v43, s0
	global_store_short v[50:51], v43, off offset:32
	s_nop 0
	v_lshlrev_b32_e32 v43, 16, v222
	v_mul_f32_e32 v54, 0xbfb8aa3b, v43
	v_exp_f32_e32 v54, v54
	s_nop 0
	v_add_f32_e32 v54, 1.0, v54
	v_div_scale_f32 v55, s[0:1], v54, v54, v43
	v_rcp_f32_e32 v58, v55
	s_nop 0
	v_fma_f32 v59, -v55, v58, 1.0
	v_fmac_f32_e32 v58, v59, v58
	v_div_scale_f32 v59, vcc, v43, v54, v43
	v_mul_f32_e32 v62, v59, v58
	v_fma_f32 v63, -v55, v62, v59
	v_fmac_f32_e32 v62, v63, v58
	v_fma_f32 v55, -v55, v62, v59
	v_div_fmas_f32 v55, v55, v58, v62
	v_div_fixup_f32 v43, v55, v54, v43
	v_mul_f32_e32 v42, v42, v43
	v_cvt_pk_bf16_f32 v42, v42, s0
	global_store_short v[50:51], v42, off offset:64
	s_nop 0
	v_lshlrev_b32_e32 v42, 16, v223
	v_mul_f32_e32 v39, 0xbfb8aa3b, v42
	v_exp_f32_e32 v39, v39
	s_nop 0
	v_add_f32_e32 v39, 1.0, v39
	v_div_scale_f32 v43, s[0:1], v39, v39, v42
	v_rcp_f32_e32 v46, v43
	s_nop 0
	v_fma_f32 v47, -v43, v46, 1.0
	v_fmac_f32_e32 v46, v47, v46
	v_div_scale_f32 v47, vcc, v42, v39, v42
	v_mul_f32_e32 v54, v47, v46
	v_fma_f32 v55, -v43, v54, v47
	v_fmac_f32_e32 v54, v55, v46
	v_fma_f32 v43, -v43, v54, v47
	v_div_fmas_f32 v43, v43, v46, v54
	v_div_fixup_f32 v39, v43, v39, v42
	v_mul_f32_e32 v38, v38, v39
	v_cvt_pk_bf16_f32 v38, v38, s0
	global_store_short v[50:51], v38, off offset:96
	v_cvt_f32_i32_e32 v38, v126
	v_mov_b32_e32 v39, v36
	v_mov_b32_e32 v42, v48
	v_mov_b32_e32 v43, v44
	v_mul_f32_e32 v38, v38, v131
	v_mul_f32_e32 v38, 0xbfb8aa3b, v38
	v_exp_f32_e32 v47, v38
	v_sub_u32_e32 v38, 0x80, v127
	v_cvt_f32_i32_e32 v38, v38
	v_mov_b32_e32 v55, v64
	v_mov_b32_e32 v51, v88
	v_mul_f32_e32 v38, v38, v130
	v_mul_f32_e32 v38, 0xbfb8aa3b, v38
	v_exp_f32_e32 v46, v38
	v_mov_b32_e32 v38, v40
	v_pk_mul_f32 v[38:39], v[46:47], v[38:39]
	s_nop 0
	v_add_f32_e32 v36, v39, v84
	v_pk_mul_f32 v[42:43], v[46:47], v[42:43]
	v_add_f32_e32 v38, v38, v36
	v_add_f32_e32 v36, v43, v96
	v_add_f32_e32 v58, v42, v36
	v_mov_b32_e32 v42, v56
	v_mov_b32_e32 v43, v52
	v_pk_mul_f32 v[42:43], v[46:47], v[42:43]
	v_mul_f32_e32 v50, v58, v58
	v_add_f32_e32 v36, v43, v92
	v_add_f32_e32 v42, v42, v36
	v_mov_b32_e32 v39, v47
	v_mov_b32_e32 v54, v38
	v_pk_fma_f32 v[50:51], v[38:39], v[54:55], v[50:51]
	v_mov_b32_e32 v43, v46
	v_mov_b32_e32 v46, v42
	v_mov_b32_e32 v47, v60
	v_pk_fma_f32 v[46:47], v[42:43], v[46:47], v[50:51]
	v_add_u32_e32 v50, s6, v127
	v_mad_i64_i32 v[54:55], s[0:1], v50, s3, v[98:99]
	v_lshl_add_u64 v[54:55], v[54:55], 0, s[26:27]
	v_lshl_add_u64 v[62:63], v[54:55], 0, v[0:1]
	v_lshl_add_u64 v[54:55], v[62:63], 0, s[10:11]
	v_add_co_u32_e32 v62, vcc, s7, v62
	v_ashrrev_i32_e32 v51, 31, v50
	s_nop 0
	v_addc_co_u32_e32 v63, vcc, 0, v63, vcc
	v_lshlrev_b64 v[50:51], 11, v[50:51]
	v_lshl_add_u64 v[50:51], s[4:5], 0, v[50:51]
	v_lshl_add_u64 v[50:51], v[50:51], 0, v[0:1]
	s_nop 0
	v_lshlrev_b32_e32 v36, 16, v224
	v_mul_f32_e32 v39, 0xbfb8aa3b, v36
	v_exp_f32_e32 v39, v39
	s_nop 0
	v_add_f32_e32 v39, 1.0, v39
	v_div_scale_f32 v40, s[0:1], v39, v39, v36
	v_rcp_f32_e32 v43, v40
	s_nop 0
	v_fma_f32 v44, -v40, v43, 1.0
	v_fmac_f32_e32 v43, v44, v43
	v_div_scale_f32 v44, vcc, v36, v39, v36
	v_mul_f32_e32 v48, v44, v43
	v_fma_f32 v52, -v40, v48, v44
	v_fmac_f32_e32 v48, v52, v43
	v_fma_f32 v40, -v40, v48, v44
	v_div_fmas_f32 v40, v40, v43, v48
	v_div_fixup_f32 v39, v40, v39, v36
	s_nop 0
	v_lshlrev_b32_e32 v36, 16, v225
	v_mul_f32_e32 v40, 0xbfb8aa3b, v36
	v_exp_f32_e32 v40, v40
	s_nop 0
	v_add_f32_e32 v40, 1.0, v40
	v_div_scale_f32 v43, s[0:1], v40, v40, v36
	v_rcp_f32_e32 v44, v43
	s_nop 0
	v_fma_f32 v48, -v43, v44, 1.0
	v_fmac_f32_e32 v44, v48, v44
	v_div_scale_f32 v48, vcc, v36, v40, v36
	v_mul_f32_e32 v52, v48, v44
	v_fma_f32 v56, -v43, v52, v48
	v_fmac_f32_e32 v52, v56, v44
	v_fma_f32 v43, -v43, v52, v48
	v_div_fmas_f32 v43, v43, v44, v52
	v_div_fixup_f32 v43, v43, v40, v36
	s_nop 0
	v_lshlrev_b32_e32 v36, 16, v226
	v_mul_f32_e32 v40, 0xbfb8aa3b, v36
	v_exp_f32_e32 v40, v40
	s_nop 0
	v_add_f32_e32 v40, 1.0, v40
	v_div_scale_f32 v44, s[0:1], v40, v40, v36
	v_rcp_f32_e32 v48, v44
	s_nop 0
	v_fma_f32 v52, -v44, v48, 1.0
	v_fmac_f32_e32 v48, v52, v48
	v_div_scale_f32 v52, vcc, v36, v40, v36
	v_mul_f32_e32 v56, v52, v48
	v_fma_f32 v59, -v44, v56, v52
	v_fmac_f32_e32 v56, v59, v48
	v_fma_f32 v44, -v44, v56, v52
	v_div_fmas_f32 v44, v44, v48, v56
	v_div_fixup_f32 v56, v44, v40, v36
	s_nop 0
	v_lshlrev_b32_e32 v36, 16, v227
	v_mul_f32_e32 v40, 0xbfb8aa3b, v36
	v_exp_f32_e32 v40, v40
	s_nop 0
	v_add_f32_e32 v40, 1.0, v40
	v_div_scale_f32 v44, s[0:1], v40, v40, v36
	v_rcp_f32_e32 v48, v44
	s_nop 0
	v_fma_f32 v52, -v44, v48, 1.0
	v_fmac_f32_e32 v48, v52, v48
	v_div_scale_f32 v52, vcc, v36, v40, v36
	v_mul_f32_e32 v54, v52, v48
	v_fma_f32 v55, -v44, v54, v52
	v_fmac_f32_e32 v54, v55, v48
	v_fma_f32 v44, -v44, v54, v52
	v_div_fmas_f32 v44, v44, v48, v54
	v_div_fixup_f32 v59, v44, v40, v36
	v_add_u32_e32 v36, 4, v132
	v_cvt_f32_i32_e32 v36, v36
	v_mov_b32_e32 v44, v49
	v_mov_b32_e32 v52, v57
	v_mul_f32_e32 v36, v36, v131
	v_mul_f32_e32 v36, 0xbfb8aa3b, v36
	v_exp_f32_e32 v55, v36
	v_sub_u32_e32 v36, 0x80, v126
	v_cvt_f32_i32_e32 v36, v36
	v_mov_b32_e32 v49, v55
	v_mul_f32_e32 v36, v36, v130
	v_mul_f32_e32 v36, 0xbfb8aa3b, v36
	v_exp_f32_e32 v54, v36
	v_mov_b32_e32 v36, v41
	v_pk_mul_f32 v[36:37], v[54:55], v[36:37]
	s_nop 0
	v_add_f32_e32 v37, v37, v85
	v_add_f32_e32 v48, v36, v37
	v_pk_mul_f32 v[36:37], v[54:55], v[44:45]
	v_mov_b32_e32 v64, v48
	v_add_f32_e32 v37, v37, v97
	v_add_f32_e32 v62, v36, v37
	v_pk_mul_f32 v[36:37], v[54:55], v[52:53]
	v_mul_f32_e32 v88, v62, v62
	v_add_f32_e32 v37, v37, v93
	v_add_f32_e32 v40, v36, v37
	v_pk_fma_f32 v[36:37], v[48:49], v[64:65], v[88:89]
	v_mov_b32_e32 v41, v54
	v_mov_b32_e32 v60, v40
	v_pk_fma_f32 v[36:37], v[40:41], v[60:61], v[36:37]
	v_mov_b32_e32 v45, v47
	v_mov_b32_e32 v44, v37
	v_mov_b32_e32 v52, v36
	v_mov_b32_e32 v53, v46
	v_pk_fma_f32 v[44:45], v[44:45], v[44:45], v[52:53]
	s_nop 1
	v_add_f32_dpp v44, v44, v44 quad_perm:[1,0,3,2] row_mask:0xf bank_mask:0xf
	v_add_f32_dpp v45, v45, v45 quad_perm:[1,0,3,2] row_mask:0xf bank_mask:0xf
	s_nop 0
	v_add_f32_dpp v44, v44, v44 quad_perm:[2,3,0,1] row_mask:0xf bank_mask:0xf
	v_add_f32_dpp v45, v45, v45 quad_perm:[2,3,0,1] row_mask:0xf bank_mask:0xf
	s_nop 0
	v_add_f32_dpp v44, v44, v44 row_half_mirror row_mask:0xf bank_mask:0xf
	v_add_f32_dpp v45, v45, v45 row_half_mirror row_mask:0xf bank_mask:0xf
	s_nop 0
	v_add_f32_dpp v44, v44, v44 row_mirror row_mask:0xf bank_mask:0xf
	v_add_f32_dpp v45, v45, v45 row_mirror row_mask:0xf bank_mask:0xf
	s_nop 0
	s_nop 0
	v_pk_fma_f32 v[44:45], v[44:45], s[12:13], v[34:35] op_sel_hi:[1,0,0]
	s_nop 0
	v_mul_f32_e32 v36, 0x4b800000, v45
	v_cmp_gt_f32_e64 s[0:1], s8, v45
	v_cmp_gt_f32_e32 vcc, s8, v44
	s_nop 0
	v_cndmask_b32_e64 v36, v45, v36, s[0:1]
	v_rsq_f32_e32 v36, v36
	s_nop 0
	v_mul_f32_e32 v41, 0x45800000, v36
	v_cndmask_b32_e64 v36, v36, v41, s[0:1]
	v_mul_f32_e32 v38, v38, v36
	v_mul_f32_e32 v38, v39, v38
	v_cvt_pk_bf16_f32 v38, v38, s0
	global_store_short v[50:51], v38, off
	v_mul_f32_e32 v38, v58, v36
	v_mul_f32_e32 v38, v38, v43
	v_cvt_pk_bf16_f32 v38, v38, s0
	global_store_short v[50:51], v38, off offset:32
	v_mul_f32_e32 v38, v42, v36
	v_mul_f32_e32 v36, v47, v36
	v_mul_f32_e32 v36, v36, v59
	v_cvt_pk_bf16_f32 v36, v36, s0
	global_store_short v[50:51], v36, off offset:96
	v_mul_f32_e32 v36, 0x4b800000, v44
	v_cndmask_b32_e32 v36, v44, v36, vcc
	v_rsq_f32_e32 v36, v36
	v_mul_f32_e32 v38, v38, v56
	v_cvt_pk_bf16_f32 v38, v38, s0
	global_store_short v[50:51], v38, off offset:64
	v_mul_f32_e32 v38, 0x45800000, v36
	v_cndmask_b32_e32 v36, v36, v38, vcc
	v_add_u32_e32 v38, s6, v126
	v_mad_i64_i32 v[42:43], s[0:1], v38, s3, v[98:99]
	v_ashrrev_i32_e32 v39, 31, v38
	v_lshl_add_u64 v[42:43], v[42:43], 0, s[26:27]
	v_lshlrev_b64 v[38:39], 11, v[38:39]
	v_lshl_add_u64 v[42:43], v[42:43], 0, v[0:1]
	v_lshl_add_u64 v[44:45], s[4:5], 0, v[38:39]
	v_lshl_add_u64 v[38:39], v[42:43], 0, s[10:11]
	v_add_co_u32_e32 v42, vcc, s7, v42
	v_mul_f32_e32 v40, v40, v36
	s_nop 0
	v_addc_co_u32_e32 v43, vcc, 0, v43, vcc
	v_mul_f32_e32 v42, v48, v36
	s_nop 0
	v_lshlrev_b32_e32 v41, 16, v228
	v_mul_f32_e32 v43, 0xbfb8aa3b, v41
	v_exp_f32_e32 v43, v43
	s_nop 0
	v_add_f32_e32 v43, 1.0, v43
	v_div_scale_f32 v46, s[0:1], v43, v43, v41
	v_rcp_f32_e32 v47, v46
	s_nop 0
	v_fma_f32 v48, -v46, v47, 1.0
	v_fmac_f32_e32 v47, v48, v47
	v_div_scale_f32 v48, vcc, v41, v43, v41
	v_mul_f32_e32 v49, v48, v47
	v_fma_f32 v50, -v46, v49, v48
	v_fmac_f32_e32 v49, v50, v47
	v_fma_f32 v46, -v46, v49, v48
	v_div_fmas_f32 v46, v46, v47, v49
	v_div_fixup_f32 v41, v46, v43, v41
	v_mul_f32_e32 v41, v41, v42
	v_cvt_pk_bf16_f32 v41, v41, s0
	v_lshl_add_u64 v[42:43], v[44:45], 0, v[0:1]
	global_store_short v[42:43], v41, off
	v_mul_f32_e32 v44, v62, v36
	v_mul_f32_e32 v36, v37, v36
	s_nop 0
	v_lshlrev_b32_e32 v41, 16, v229
	v_mul_f32_e32 v45, 0xbfb8aa3b, v41
	v_exp_f32_e32 v45, v45
	s_nop 0
	v_add_f32_e32 v45, 1.0, v45
	v_div_scale_f32 v46, s[0:1], v45, v45, v41
	v_rcp_f32_e32 v47, v46
	s_nop 0
	v_fma_f32 v48, -v46, v47, 1.0
	v_fmac_f32_e32 v47, v48, v47
	v_div_scale_f32 v48, vcc, v41, v45, v41
	v_mul_f32_e32 v49, v48, v47
	v_fma_f32 v50, -v46, v49, v48
	v_fmac_f32_e32 v49, v50, v47
	v_fma_f32 v46, -v46, v49, v48
	v_div_fmas_f32 v46, v46, v47, v49
	v_div_fixup_f32 v41, v46, v45, v41
	v_mul_f32_e32 v41, v44, v41
	v_cvt_pk_bf16_f32 v41, v41, s0
	global_store_short v[42:43], v41, off offset:32
	s_nop 0
	v_lshlrev_b32_e32 v41, 16, v230
	v_mul_f32_e32 v44, 0xbfb8aa3b, v41
	v_exp_f32_e32 v44, v44
	s_nop 0
	v_lshlrev_b32_e32 v38, 16, v231
	v_add_f32_e32 v44, 1.0, v44
	v_div_scale_f32 v45, s[0:1], v44, v44, v41
	v_rcp_f32_e32 v46, v45
	v_mul_f32_e32 v37, 0xbfb8aa3b, v38
	v_exp_f32_e32 v37, v37
	v_fma_f32 v47, -v45, v46, 1.0
	v_fmac_f32_e32 v46, v47, v46
	v_div_scale_f32 v47, vcc, v41, v44, v41
	v_mul_f32_e32 v48, v47, v46
	v_fma_f32 v49, -v45, v48, v47
	v_fmac_f32_e32 v48, v49, v46
	v_fma_f32 v45, -v45, v48, v47
	v_div_fmas_f32 v45, v45, v46, v48
	v_div_fixup_f32 v41, v45, v44, v41
	v_mul_f32_e32 v40, v40, v41
	v_add_f32_e32 v37, 1.0, v37
	v_cvt_pk_bf16_f32 v40, v40, s0
	v_div_scale_f32 v39, s[0:1], v37, v37, v38
	global_store_short v[42:43], v40, off offset:64
	v_rcp_f32_e32 v40, v39
	s_nop 0
	v_fma_f32 v41, -v39, v40, 1.0
	v_fmac_f32_e32 v40, v41, v40
	v_div_scale_f32 v41, vcc, v38, v37, v38
	v_mul_f32_e32 v44, v41, v40
	v_fma_f32 v45, -v39, v44, v41
	v_fmac_f32_e32 v44, v45, v40
	v_fma_f32 v39, -v39, v44, v41
	v_div_fmas_f32 v39, v39, v40, v44
	v_div_fixup_f32 v37, v39, v37, v38
	v_mul_f32_e32 v36, v36, v37
	v_cvt_pk_bf16_f32 v36, v36, s0
	global_store_short v[42:43], v36, off offset:96
	v_cvt_f32_i32_e32 v36, v112
	v_mov_b32_e32 v37, v2
	v_mov_b32_e32 v38, v14
	v_mov_b32_e32 v39, v10
	v_mul_f32_e32 v36, v36, v131
	v_mul_f32_e32 v36, 0xbfb8aa3b, v36
	v_exp_f32_e32 v41, v36
	v_sub_u32_e32 v36, 0x80, v115
	v_cvt_f32_i32_e32 v36, v36
	v_mov_b32_e32 v45, v30
	v_mov_b32_e32 v43, v70
	v_mul_f32_e32 v36, v36, v130
	v_mul_f32_e32 v36, 0xbfb8aa3b, v36
	v_exp_f32_e32 v40, v36
	v_mov_b32_e32 v36, v6
	v_pk_mul_f32 v[36:37], v[40:41], v[36:37]
	s_nop 0
	v_add_f32_e32 v2, v37, v66
	v_pk_mul_f32 v[38:39], v[40:41], v[38:39]
	v_add_f32_e32 v36, v36, v2
	v_add_f32_e32 v2, v39, v78
	v_add_f32_e32 v46, v38, v2
	v_mov_b32_e32 v38, v22
	v_mov_b32_e32 v39, v18
	v_pk_mul_f32 v[38:39], v[40:41], v[38:39]
	v_mul_f32_e32 v42, v46, v46
	v_add_f32_e32 v2, v39, v74
	v_add_f32_e32 v38, v38, v2
	v_mov_b32_e32 v37, v41
	v_mov_b32_e32 v44, v36
	v_pk_fma_f32 v[42:43], v[36:37], v[44:45], v[42:43]
	v_mov_b32_e32 v39, v40
	v_mov_b32_e32 v40, v38
	v_mov_b32_e32 v41, v26
	v_pk_fma_f32 v[40:41], v[38:39], v[40:41], v[42:43]
	v_add_u32_e32 v42, s6, v115
	v_mad_i64_i32 v[44:45], s[0:1], v42, s3, v[98:99]
	v_lshl_add_u64 v[44:45], v[44:45], 0, s[26:27]
	v_lshl_add_u64 v[48:49], v[44:45], 0, v[0:1]
	v_lshl_add_u64 v[44:45], v[48:49], 0, s[10:11]
	v_add_co_u32_e32 v48, vcc, s7, v48
	v_ashrrev_i32_e32 v43, 31, v42
	s_nop 0
	v_addc_co_u32_e32 v49, vcc, 0, v49, vcc
	v_lshlrev_b64 v[42:43], 11, v[42:43]
	v_lshl_add_u64 v[42:43], s[4:5], 0, v[42:43]
	v_lshl_add_u64 v[42:43], v[42:43], 0, v[0:1]
	s_waitcnt vmcnt(16)
	v_lshlrev_b32_e32 v2, 16, v176
	v_mul_f32_e32 v6, 0xbfb8aa3b, v2
	v_exp_f32_e32 v6, v6
	s_nop 0
	v_add_f32_e32 v6, 1.0, v6
	v_div_scale_f32 v10, s[0:1], v6, v6, v2
	v_rcp_f32_e32 v14, v10
	s_nop 0
	v_fma_f32 v18, -v10, v14, 1.0
	v_fmac_f32_e32 v14, v18, v14
	v_div_scale_f32 v18, vcc, v2, v6, v2
	v_mul_f32_e32 v22, v18, v14
	v_fma_f32 v26, -v10, v22, v18
	v_fmac_f32_e32 v22, v26, v14
	v_fma_f32 v10, -v10, v22, v18
	v_div_fmas_f32 v10, v10, v14, v22
	v_div_fixup_f32 v22, v10, v6, v2
	s_nop 0
	v_lshlrev_b32_e32 v2, 16, v177
	v_mul_f32_e32 v6, 0xbfb8aa3b, v2
	v_exp_f32_e32 v6, v6
	s_nop 0
	v_add_f32_e32 v6, 1.0, v6
	v_div_scale_f32 v10, s[0:1], v6, v6, v2
	v_rcp_f32_e32 v14, v10
	s_nop 0
	v_fma_f32 v18, -v10, v14, 1.0
	v_fmac_f32_e32 v14, v18, v14
	v_div_scale_f32 v18, vcc, v2, v6, v2
	v_mul_f32_e32 v26, v18, v14
	v_fma_f32 v30, -v10, v26, v18
	v_fmac_f32_e32 v26, v30, v14
	v_fma_f32 v10, -v10, v26, v18
	v_div_fmas_f32 v10, v10, v14, v26
	v_div_fixup_f32 v37, v10, v6, v2
	s_nop 0
	v_lshlrev_b32_e32 v2, 16, v178
	v_mul_f32_e32 v6, 0xbfb8aa3b, v2
	v_exp_f32_e32 v6, v6
	s_nop 0
	v_add_f32_e32 v6, 1.0, v6
	v_div_scale_f32 v10, s[0:1], v6, v6, v2
	v_rcp_f32_e32 v14, v10
	s_nop 0
	v_fma_f32 v18, -v10, v14, 1.0
	v_fmac_f32_e32 v14, v18, v14
	v_div_scale_f32 v18, vcc, v2, v6, v2
	v_mul_f32_e32 v26, v18, v14
	v_fma_f32 v30, -v10, v26, v18
	v_fmac_f32_e32 v26, v30, v14
	v_fma_f32 v10, -v10, v26, v18
	v_div_fmas_f32 v10, v10, v14, v26
	v_div_fixup_f32 v39, v10, v6, v2
	s_nop 0
	v_lshlrev_b32_e32 v2, 16, v179
	v_mul_f32_e32 v6, 0xbfb8aa3b, v2
	v_exp_f32_e32 v6, v6
	s_nop 0
	v_add_f32_e32 v6, 1.0, v6
	v_div_scale_f32 v10, s[0:1], v6, v6, v2
	v_rcp_f32_e32 v14, v10
	s_nop 0
	v_fma_f32 v18, -v10, v14, 1.0
	v_fmac_f32_e32 v14, v18, v14
	v_div_scale_f32 v18, vcc, v2, v6, v2
	v_mul_f32_e32 v26, v18, v14
	v_fma_f32 v30, -v10, v26, v18
	v_fmac_f32_e32 v26, v30, v14
	v_fma_f32 v10, -v10, v26, v18
	v_div_fmas_f32 v10, v10, v14, v26
	v_div_fixup_f32 v47, v10, v6, v2
	v_cvt_f32_i32_e32 v2, v111
	v_mov_b32_e32 v10, v15
	v_mov_b32_e32 v18, v23
	v_mul_f32_e32 v2, v2, v131
	v_mul_f32_e32 v2, 0xbfb8aa3b, v2
	v_exp_f32_e32 v45, v2
	v_sub_u32_e32 v2, 0x80, v112
	v_cvt_f32_i32_e32 v2, v2
	v_mov_b32_e32 v15, v45
	v_mul_f32_e32 v2, v2, v130
	v_mul_f32_e32 v2, 0xbfb8aa3b, v2
	v_exp_f32_e32 v44, v2
	v_mov_b32_e32 v2, v7
	v_pk_mul_f32 v[2:3], v[44:45], v[2:3]
	s_nop 0
	v_add_f32_e32 v3, v3, v67
	v_add_f32_e32 v14, v2, v3
	v_pk_mul_f32 v[2:3], v[44:45], v[10:11]
	v_mov_b32_e32 v30, v14
	v_add_f32_e32 v3, v3, v79
	v_add_f32_e32 v48, v2, v3
	v_pk_mul_f32 v[2:3], v[44:45], v[18:19]
	v_mul_f32_e32 v70, v48, v48
	v_add_f32_e32 v3, v3, v75
	v_add_f32_e32 v6, v2, v3
	v_pk_fma_f32 v[2:3], v[14:15], v[30:31], v[70:71]
	v_mov_b32_e32 v7, v44
	v_mov_b32_e32 v26, v6
	v_pk_fma_f32 v[2:3], v[6:7], v[26:27], v[2:3]
	v_mov_b32_e32 v11, v41
	v_mov_b32_e32 v10, v3
	v_mov_b32_e32 v18, v2
	v_mov_b32_e32 v19, v40
	v_pk_fma_f32 v[10:11], v[10:11], v[10:11], v[18:19]
	s_nop 1
	v_add_f32_dpp v10, v10, v10 quad_perm:[1,0,3,2] row_mask:0xf bank_mask:0xf
	v_add_f32_dpp v11, v11, v11 quad_perm:[1,0,3,2] row_mask:0xf bank_mask:0xf
	s_nop 0
	v_add_f32_dpp v10, v10, v10 quad_perm:[2,3,0,1] row_mask:0xf bank_mask:0xf
	v_add_f32_dpp v11, v11, v11 quad_perm:[2,3,0,1] row_mask:0xf bank_mask:0xf
	s_nop 0
	v_add_f32_dpp v10, v10, v10 row_half_mirror row_mask:0xf bank_mask:0xf
	v_add_f32_dpp v11, v11, v11 row_half_mirror row_mask:0xf bank_mask:0xf
	s_nop 0
	v_add_f32_dpp v10, v10, v10 row_mirror row_mask:0xf bank_mask:0xf
	v_add_f32_dpp v11, v11, v11 row_mirror row_mask:0xf bank_mask:0xf
	s_nop 0
	s_nop 0
	v_pk_fma_f32 v[10:11], v[10:11], s[12:13], v[34:35] op_sel_hi:[1,0,0]
	s_nop 0
	v_mul_f32_e32 v2, 0x4b800000, v11
	v_cmp_gt_f32_e64 s[0:1], s8, v11
	v_cmp_gt_f32_e32 vcc, s8, v10
	s_nop 0
	v_cndmask_b32_e64 v2, v11, v2, s[0:1]
	v_rsq_f32_e32 v2, v2
	s_nop 0
	v_mul_f32_e32 v7, 0x45800000, v2
	v_cndmask_b32_e64 v2, v2, v7, s[0:1]
	v_mul_f32_e32 v7, v36, v2
	v_mul_f32_e32 v7, v22, v7
	v_cvt_pk_bf16_f32 v7, v7, s0
	global_store_short v[42:43], v7, off
	v_mul_f32_e32 v7, v46, v2
	v_mul_f32_e32 v7, v7, v37
	v_cvt_pk_bf16_f32 v7, v7, s0
	global_store_short v[42:43], v7, off offset:32
	v_mul_f32_e32 v7, v38, v2
	v_mul_f32_e32 v2, v41, v2
	v_mul_f32_e32 v2, v2, v47
	v_cvt_pk_bf16_f32 v2, v2, s0
	global_store_short v[42:43], v2, off offset:96
	v_mul_f32_e32 v2, 0x4b800000, v10
	v_cndmask_b32_e32 v2, v10, v2, vcc
	v_rsq_f32_e32 v2, v2
	v_mul_f32_e32 v7, v7, v39
	v_add_u32_e32 v10, s6, v112
	v_cvt_pk_bf16_f32 v7, v7, s0
	v_mad_i64_i32 v[18:19], s[0:1], v10, s3, v[98:99]
	v_ashrrev_i32_e32 v11, 31, v10
	v_lshl_add_u64 v[18:19], v[18:19], 0, s[26:27]
	global_store_short v[42:43], v7, off offset:64
	v_mul_f32_e32 v7, 0x45800000, v2
	v_lshlrev_b64 v[10:11], 11, v[10:11]
	v_lshl_add_u64 v[18:19], v[18:19], 0, v[0:1]
	v_cndmask_b32_e32 v2, v2, v7, vcc
	v_lshl_add_u64 v[22:23], s[4:5], 0, v[10:11]
	v_lshl_add_u64 v[10:11], v[18:19], 0, s[10:11]
	v_add_co_u32_e32 v18, vcc, s7, v18
	v_mul_f32_e32 v14, v14, v2
	s_nop 0
	v_addc_co_u32_e32 v19, vcc, 0, v19, vcc
	v_mul_f32_e32 v6, v6, v2
	s_nop 0
	v_lshlrev_b32_e32 v7, 16, v180
	v_mul_f32_e32 v15, 0xbfb8aa3b, v7
	v_exp_f32_e32 v15, v15
	s_nop 0
	v_add_f32_e32 v15, 1.0, v15
	v_div_scale_f32 v18, s[0:1], v15, v15, v7
	v_rcp_f32_e32 v19, v18
	s_nop 0
	v_fma_f32 v26, -v18, v19, 1.0
	v_fmac_f32_e32 v19, v26, v19
	v_div_scale_f32 v26, vcc, v7, v15, v7
	v_mul_f32_e32 v27, v26, v19
	v_fma_f32 v30, -v18, v27, v26
	v_fmac_f32_e32 v27, v30, v19
	v_fma_f32 v18, -v18, v27, v26
	v_div_fmas_f32 v18, v18, v19, v27
	v_div_fixup_f32 v7, v18, v15, v7
	v_mul_f32_e32 v7, v7, v14
	v_cvt_pk_bf16_f32 v7, v7, s0
	v_lshl_add_u64 v[14:15], v[22:23], 0, v[0:1]
	global_store_short v[14:15], v7, off
	v_mul_f32_e32 v18, v48, v2
	v_mul_f32_e32 v2, v3, v2
	s_nop 0
	v_lshlrev_b32_e32 v7, 16, v181
	v_mul_f32_e32 v19, 0xbfb8aa3b, v7
	v_exp_f32_e32 v19, v19
	s_nop 0
	v_add_f32_e32 v19, 1.0, v19
	v_div_scale_f32 v22, s[0:1], v19, v19, v7
	v_rcp_f32_e32 v23, v22
	s_nop 0
	v_fma_f32 v26, -v22, v23, 1.0
	v_fmac_f32_e32 v23, v26, v23
	v_div_scale_f32 v26, vcc, v7, v19, v7
	v_mul_f32_e32 v27, v26, v23
	v_fma_f32 v30, -v22, v27, v26
	v_fmac_f32_e32 v27, v30, v23
	v_fma_f32 v22, -v22, v27, v26
	v_div_fmas_f32 v22, v22, v23, v27
	v_div_fixup_f32 v7, v22, v19, v7
	v_mul_f32_e32 v7, v18, v7
	v_cvt_pk_bf16_f32 v7, v7, s0
	global_store_short v[14:15], v7, off offset:32
	s_nop 0
	v_lshlrev_b32_e32 v7, 16, v182
	v_mul_f32_e32 v18, 0xbfb8aa3b, v7
	v_exp_f32_e32 v18, v18
	s_nop 0
	v_add_f32_e32 v18, 1.0, v18
	v_div_scale_f32 v19, s[0:1], v18, v18, v7
	v_rcp_f32_e32 v22, v19
	s_nop 0
	v_fma_f32 v23, -v19, v22, 1.0
	v_fmac_f32_e32 v22, v23, v22
	v_div_scale_f32 v23, vcc, v7, v18, v7
	v_mul_f32_e32 v26, v23, v22
	v_fma_f32 v27, -v19, v26, v23
	v_fmac_f32_e32 v26, v27, v22
	v_fma_f32 v19, -v19, v26, v23
	v_div_fmas_f32 v19, v19, v22, v26
	v_div_fixup_f32 v7, v19, v18, v7
	v_mul_f32_e32 v6, v6, v7
	v_cvt_pk_bf16_f32 v6, v6, s0
	global_store_short v[14:15], v6, off offset:64
	s_nop 0
	v_lshlrev_b32_e32 v6, 16, v183
	v_mul_f32_e32 v3, 0xbfb8aa3b, v6
	v_exp_f32_e32 v3, v3
	s_nop 0
	v_add_f32_e32 v3, 1.0, v3
	v_div_scale_f32 v7, s[0:1], v3, v3, v6
	v_rcp_f32_e32 v10, v7
	s_nop 0
	v_fma_f32 v11, -v7, v10, 1.0
	v_fmac_f32_e32 v10, v11, v10
	v_div_scale_f32 v11, vcc, v6, v3, v6
	v_mul_f32_e32 v18, v11, v10
	v_fma_f32 v19, -v7, v18, v11
	v_fmac_f32_e32 v18, v19, v10
	v_fma_f32 v7, -v7, v18, v11
	v_div_fmas_f32 v7, v7, v10, v18
	v_div_fixup_f32 v3, v7, v3, v6
	v_mul_f32_e32 v2, v2, v3
	v_cvt_pk_bf16_f32 v2, v2, s0
	global_store_short v[14:15], v2, off offset:96
	v_cvt_f32_i32_e32 v2, v110
	v_mov_b32_e32 v3, v4
	v_mov_b32_e32 v6, v16
	v_mov_b32_e32 v7, v12
	v_mul_f32_e32 v2, v2, v131
	v_mul_f32_e32 v2, 0xbfb8aa3b, v2
	v_exp_f32_e32 v11, v2
	v_sub_u32_e32 v2, 0x80, v111
	v_cvt_f32_i32_e32 v2, v2
	v_mov_b32_e32 v19, v32
	v_mov_b32_e32 v15, v72
	v_mul_f32_e32 v2, v2, v130
	v_mul_f32_e32 v2, 0xbfb8aa3b, v2
	v_exp_f32_e32 v10, v2
	v_mov_b32_e32 v2, v8
	v_pk_mul_f32 v[2:3], v[10:11], v[2:3]
	s_nop 0
	v_add_f32_e32 v3, v3, v68
	v_pk_mul_f32 v[6:7], v[10:11], v[6:7]
	v_add_f32_e32 v2, v2, v3
	v_add_f32_e32 v3, v7, v80
	v_add_f32_e32 v22, v6, v3
	v_mov_b32_e32 v6, v24
	v_mov_b32_e32 v7, v20
	v_pk_mul_f32 v[6:7], v[10:11], v[6:7]
	v_mul_f32_e32 v14, v22, v22
	v_add_f32_e32 v3, v7, v76
	v_add_f32_e32 v6, v6, v3
	v_mov_b32_e32 v3, v11
	v_mov_b32_e32 v18, v2
	v_pk_fma_f32 v[14:15], v[2:3], v[18:19], v[14:15]
	v_mov_b32_e32 v7, v10
	v_mov_b32_e32 v10, v6
	v_mov_b32_e32 v11, v28
	v_pk_fma_f32 v[10:11], v[6:7], v[10:11], v[14:15]
	v_add_u32_e32 v14, s6, v111
	v_mad_i64_i32 v[18:19], s[0:1], v14, s3, v[98:99]
	v_lshl_add_u64 v[18:19], v[18:19], 0, s[26:27]
	v_lshl_add_u64 v[26:27], v[18:19], 0, v[0:1]
	v_lshl_add_u64 v[18:19], v[26:27], 0, s[10:11]
	v_add_co_u32_e32 v26, vcc, s7, v26
	v_ashrrev_i32_e32 v15, 31, v14
	s_nop 0
	v_addc_co_u32_e32 v27, vcc, 0, v27, vcc
	v_lshlrev_b64 v[14:15], 11, v[14:15]
	v_lshl_add_u64 v[14:15], s[4:5], 0, v[14:15]
	v_lshl_add_u64 v[14:15], v[14:15], 0, v[0:1]
	s_nop 0
	v_lshlrev_b32_e32 v3, 16, v184
	v_mul_f32_e32 v4, 0xbfb8aa3b, v3
	v_exp_f32_e32 v4, v4
	s_nop 0
	v_add_f32_e32 v4, 1.0, v4
	v_div_scale_f32 v7, s[0:1], v4, v4, v3
	v_rcp_f32_e32 v8, v7
	s_nop 0
	v_fma_f32 v12, -v7, v8, 1.0
	v_fmac_f32_e32 v8, v12, v8
	v_div_scale_f32 v12, vcc, v3, v4, v3
	v_mul_f32_e32 v16, v12, v8
	v_fma_f32 v20, -v7, v16, v12
	v_fmac_f32_e32 v16, v20, v8
	v_fma_f32 v7, -v7, v16, v12
	v_div_fmas_f32 v7, v7, v8, v16
	v_div_fixup_f32 v3, v7, v4, v3
	s_nop 0
	v_lshlrev_b32_e32 v4, 16, v185
	v_mul_f32_e32 v7, 0xbfb8aa3b, v4
	v_exp_f32_e32 v7, v7
	s_nop 0
	v_add_f32_e32 v7, 1.0, v7
	v_div_scale_f32 v8, s[0:1], v7, v7, v4
	v_rcp_f32_e32 v12, v8
	s_nop 0
	v_fma_f32 v16, -v8, v12, 1.0
	v_fmac_f32_e32 v12, v16, v12
	v_div_scale_f32 v16, vcc, v4, v7, v4
	v_mul_f32_e32 v20, v16, v12
	v_fma_f32 v23, -v8, v20, v16
	v_fmac_f32_e32 v20, v23, v12
	v_fma_f32 v8, -v8, v20, v16
	v_div_fmas_f32 v8, v8, v12, v20
	v_div_fixup_f32 v7, v8, v7, v4
	s_nop 0
	v_lshlrev_b32_e32 v4, 16, v186
	v_mul_f32_e32 v8, 0xbfb8aa3b, v4
	v_exp_f32_e32 v8, v8
	s_nop 0
	v_add_f32_e32 v8, 1.0, v8
	v_div_scale_f32 v12, s[0:1], v8, v8, v4
	v_rcp_f32_e32 v16, v12
	s_nop 0
	v_fma_f32 v20, -v12, v16, 1.0
	v_fmac_f32_e32 v16, v20, v16
	v_div_scale_f32 v20, vcc, v4, v8, v4
	v_mul_f32_e32 v23, v20, v16
	v_fma_f32 v24, -v12, v23, v20
	v_fmac_f32_e32 v23, v24, v16
	v_fma_f32 v12, -v12, v23, v20
	v_div_fmas_f32 v12, v12, v16, v23
	v_div_fixup_f32 v23, v12, v8, v4
	s_nop 0
	v_lshlrev_b32_e32 v4, 16, v187
	v_mul_f32_e32 v8, 0xbfb8aa3b, v4
	v_exp_f32_e32 v8, v8
	s_nop 0
	v_add_f32_e32 v8, 1.0, v8
	v_div_scale_f32 v12, s[0:1], v8, v8, v4
	v_rcp_f32_e32 v16, v12
	s_nop 0
	v_fma_f32 v18, -v12, v16, 1.0
	v_fmac_f32_e32 v16, v18, v16
	v_div_scale_f32 v18, vcc, v4, v8, v4
	v_mul_f32_e32 v19, v18, v16
	v_fma_f32 v20, -v12, v19, v18
	v_fmac_f32_e32 v19, v20, v16
	v_fma_f32 v12, -v12, v19, v18
	v_div_fmas_f32 v12, v12, v16, v19
	v_div_fixup_f32 v24, v12, v8, v4
	v_add_u32_e32 v4, 20, v132
	v_cvt_f32_i32_e32 v4, v4
	v_mov_b32_e32 v12, v17
	v_mov_b32_e32 v20, v25
	v_mul_f32_e32 v4, v4, v131
	v_mul_f32_e32 v4, 0xbfb8aa3b, v4
	v_exp_f32_e32 v19, v4
	v_sub_u32_e32 v4, 0x80, v110
	v_cvt_f32_i32_e32 v4, v4
	v_mov_b32_e32 v17, v19
	v_mul_f32_e32 v4, v4, v130
	v_mul_f32_e32 v4, 0xbfb8aa3b, v4
	v_exp_f32_e32 v18, v4
	v_mov_b32_e32 v4, v9
	v_pk_mul_f32 v[4:5], v[18:19], v[4:5]
	s_nop 0
	v_add_f32_e32 v5, v5, v69
	v_add_f32_e32 v16, v4, v5
	v_pk_mul_f32 v[4:5], v[18:19], v[12:13]
	v_mov_b32_e32 v32, v16
	v_add_f32_e32 v5, v5, v81
	v_add_f32_e32 v26, v4, v5
	v_pk_mul_f32 v[4:5], v[18:19], v[20:21]
	v_mul_f32_e32 v72, v26, v26
	v_add_f32_e32 v5, v5, v77
	v_add_f32_e32 v8, v4, v5
	v_pk_fma_f32 v[4:5], v[16:17], v[32:33], v[72:73]
	v_mov_b32_e32 v9, v18
	v_mov_b32_e32 v28, v8
	v_pk_fma_f32 v[4:5], v[8:9], v[28:29], v[4:5]
	v_mov_b32_e32 v13, v11
	v_mov_b32_e32 v12, v5
	v_mov_b32_e32 v18, v4
	v_mov_b32_e32 v19, v10
	v_pk_fma_f32 v[12:13], v[12:13], v[12:13], v[18:19]
	s_nop 1
	v_add_f32_dpp v12, v12, v12 quad_perm:[1,0,3,2] row_mask:0xf bank_mask:0xf
	v_add_f32_dpp v13, v13, v13 quad_perm:[1,0,3,2] row_mask:0xf bank_mask:0xf
	s_nop 0
	v_add_f32_dpp v12, v12, v12 quad_perm:[2,3,0,1] row_mask:0xf bank_mask:0xf
	v_add_f32_dpp v13, v13, v13 quad_perm:[2,3,0,1] row_mask:0xf bank_mask:0xf
	s_nop 0
	v_add_f32_dpp v12, v12, v12 row_half_mirror row_mask:0xf bank_mask:0xf
	v_add_f32_dpp v13, v13, v13 row_half_mirror row_mask:0xf bank_mask:0xf
	s_nop 0
	v_add_f32_dpp v12, v12, v12 row_mirror row_mask:0xf bank_mask:0xf
	v_add_f32_dpp v13, v13, v13 row_mirror row_mask:0xf bank_mask:0xf
	s_nop 0
	s_nop 0
	v_pk_fma_f32 v[12:13], v[12:13], s[12:13], v[34:35] op_sel_hi:[1,0,0]
	s_nop 0
	v_mul_f32_e32 v4, 0x4b800000, v13
	v_cmp_gt_f32_e64 s[0:1], s8, v13
	v_cmp_gt_f32_e32 vcc, s8, v12
	s_nop 0
	v_cndmask_b32_e64 v4, v13, v4, s[0:1]
	v_rsq_f32_e32 v4, v4
	s_nop 0
	v_mul_f32_e32 v9, 0x45800000, v4
	v_cndmask_b32_e64 v4, v4, v9, s[0:1]
	v_mul_f32_e32 v2, v2, v4
	v_mul_f32_e32 v2, v3, v2
	v_cvt_pk_bf16_f32 v2, v2, s0
	global_store_short v[14:15], v2, off
	v_mul_f32_e32 v2, v22, v4
	v_mul_f32_e32 v2, v2, v7
	v_cvt_pk_bf16_f32 v2, v2, s0
	global_store_short v[14:15], v2, off offset:32
	v_mul_f32_e32 v2, v6, v4
	v_mul_f32_e32 v2, v2, v23
	v_cvt_pk_bf16_f32 v2, v2, s0
	global_store_short v[14:15], v2, off offset:64
	v_mul_f32_e32 v2, v11, v4
	v_mul_f32_e32 v2, v2, v24
	v_cvt_pk_bf16_f32 v2, v2, s0
	global_store_short v[14:15], v2, off offset:96
	v_mul_f32_e32 v2, 0x4b800000, v12
	v_cndmask_b32_e32 v2, v12, v2, vcc
	v_rsq_f32_e32 v2, v2
	s_nop 0
	v_mul_f32_e32 v3, 0x45800000, v2
	v_cndmask_b32_e32 v4, v2, v3, vcc
	v_add_u32_e32 v2, s6, v110
	v_mad_i64_i32 v[6:7], s[0:1], v2, s3, v[98:99]
	v_lshl_add_u64 v[6:7], v[6:7], 0, s[26:27]
	v_lshl_add_u64 v[10:11], v[6:7], 0, v[0:1]
	v_lshl_add_u64 v[6:7], v[10:11], 0, s[10:11]
	v_add_co_u32_e32 v10, vcc, s7, v10
	v_ashrrev_i32_e32 v3, 31, v2
	s_nop 0
	v_addc_co_u32_e32 v11, vcc, 0, v11, vcc
	v_lshlrev_b64 v[2:3], 11, v[2:3]
	v_lshl_add_u64 v[2:3], s[4:5], 0, v[2:3]
	v_lshl_add_u64 v[2:3], v[2:3], 0, v[0:1]
	v_mul_f32_e32 v10, v16, v4
	v_mul_f32_e32 v8, v8, v4
	s_nop 0
	v_lshlrev_b32_e32 v9, 16, v188
	v_mul_f32_e32 v11, 0xbfb8aa3b, v9
	v_exp_f32_e32 v11, v11
	s_nop 0
	v_lshlrev_b32_e32 v0, 16, v189
	v_add_f32_e32 v11, 1.0, v11
	v_div_scale_f32 v12, s[0:1], v11, v11, v9
	v_rcp_f32_e32 v13, v12
	s_nop 0
	v_fma_f32 v14, -v12, v13, 1.0
	v_fmac_f32_e32 v13, v14, v13
	v_div_scale_f32 v14, vcc, v9, v11, v9
	v_mul_f32_e32 v15, v14, v13
	v_fma_f32 v16, -v12, v15, v14
	v_fmac_f32_e32 v15, v16, v13
	v_fma_f32 v12, -v12, v15, v14
	v_div_fmas_f32 v12, v12, v13, v15
	v_div_fixup_f32 v9, v12, v11, v9
	v_mul_f32_e32 v9, v9, v10
	v_mul_f32_e32 v10, 0xbfb8aa3b, v0
	v_exp_f32_e32 v10, v10
	v_cvt_pk_bf16_f32 v9, v9, s0
	global_store_short v[2:3], v9, off
	v_mul_f32_e32 v9, v26, v4
	v_add_f32_e32 v10, 1.0, v10
	v_div_scale_f32 v11, s[0:1], v10, v10, v0
	v_rcp_f32_e32 v12, v11
	v_mul_f32_e32 v4, v5, v4
	v_fma_f32 v13, -v11, v12, 1.0
	v_fmac_f32_e32 v12, v13, v12
	v_div_scale_f32 v13, vcc, v0, v10, v0
	v_mul_f32_e32 v14, v13, v12
	v_fma_f32 v15, -v11, v14, v13
	v_fmac_f32_e32 v14, v15, v12
	v_fma_f32 v11, -v11, v14, v13
	v_div_fmas_f32 v11, v11, v12, v14
	v_div_fixup_f32 v0, v11, v10, v0
	v_mul_f32_e32 v0, v9, v0
	v_cvt_pk_bf16_f32 v0, v0, s0
	global_store_short v[2:3], v0, off offset:32
	s_nop 0
	v_lshlrev_b32_e32 v0, 16, v190
	v_mul_f32_e32 v9, 0xbfb8aa3b, v0
	v_exp_f32_e32 v9, v9
	s_nop 0
	v_add_f32_e32 v9, 1.0, v9
	v_div_scale_f32 v10, s[0:1], v9, v9, v0
	v_rcp_f32_e32 v11, v10
	s_nop 0
	v_fma_f32 v12, -v10, v11, 1.0
	v_fmac_f32_e32 v11, v12, v11
	v_div_scale_f32 v12, vcc, v0, v9, v0
	v_mul_f32_e32 v13, v12, v11
	v_fma_f32 v14, -v10, v13, v12
	v_fmac_f32_e32 v13, v14, v11
	v_fma_f32 v10, -v10, v13, v12
	v_div_fmas_f32 v10, v10, v11, v13
	v_div_fixup_f32 v0, v10, v9, v0
	v_mul_f32_e32 v0, v8, v0
	v_cvt_pk_bf16_f32 v0, v0, s0
	global_store_short v[2:3], v0, off offset:64
	s_nop 0
	v_lshlrev_b32_e32 v0, 16, v191
	v_mul_f32_e32 v5, 0xbfb8aa3b, v0
	v_exp_f32_e32 v5, v5
	s_nop 0
	v_add_f32_e32 v5, 1.0, v5
	v_div_scale_f32 v6, s[0:1], v5, v5, v0
	v_rcp_f32_e32 v7, v6
	s_nop 0
	v_fma_f32 v8, -v6, v7, 1.0
	v_fmac_f32_e32 v7, v8, v7
	v_div_scale_f32 v8, vcc, v0, v5, v0
	v_mul_f32_e32 v9, v8, v7
	v_fma_f32 v10, -v6, v9, v8
	v_fmac_f32_e32 v9, v10, v7
	v_fma_f32 v6, -v6, v9, v8
	v_div_fmas_f32 v6, v6, v7, v9
	v_div_fixup_f32 v0, v6, v5, v0
	v_mul_f32_e32 v0, v4, v0
	v_cvt_pk_bf16_f32 v0, v0, s0
	global_store_short v[2:3], v0, off offset:96
	s_barrier
	s_branch .LBB0_184
